# v32 plus select compaction: s_and into vcc directly feeding s_and_saveexec (one fewer dependent SALU hop per register)
# speedup vs baseline: 1.0011x; 1.0007x over previous
; template <int NR>
; DI u64 select_wave(float* scw, int nreg, int lane) {
;     ...
;   if (!exact && lo < hi) {
;     unsigned* cand = reinterpret_cast<unsigned*>(scw);
;     int base = 0;
; #pragma unroll
;     for (int r = 0; r < NR; ++r) {
;       const bool pred = (key[r] >= lo) && (key[r] <= hi);
;       const u64 bal = __builtin_amdgcn_ballot_w64(pred);
;       const int pos = base + __builtin_amdgcn_mbcnt_hi((unsigned)(bal >> 32), __builtin_amdgcn_mbcnt_lo((unsigned)bal, 0u));
;       if (pred) cand[pos] = key[r];
;       base += __builtin_popcountll(bal);
;     }
.LBB0_225:
	s_mov_b64 s[2:3], -1
	s_and_b64 vcc, exec, s[0:1]
	s_cbranch_vccnz .LBB0_362
	s_cmp_ge_u32 s81, s80
	s_mov_b64 s[0:1], 0
	s_cbranch_scc1 .LBB0_363
	v_cmp_le_u32_e32 vcc, s81, v50
	v_cmp_ge_u32_e64 s[0:1], s80, v50
	s_and_b64 vcc, vcc, s[0:1]
	s_and_saveexec_b64 s[0:1], vcc
	v_mbcnt_lo_u32_b32 v26, vcc_lo, 0
	v_mbcnt_hi_u32_b32 v26, vcc_hi, v26
	v_lshl_add_u32 v26, v26, 2, s15
	ds_write_b32 v26, v50
	s_or_b64 exec, exec, s[0:1]
	s_bcnt1_i32_b64 s6, vcc
	v_cmp_le_u32_e32 vcc, s81, v49
	v_cmp_ge_u32_e64 s[0:1], s80, v49
	s_and_b64 vcc, vcc, s[0:1]
	s_and_saveexec_b64 s[0:1], vcc
	v_mbcnt_lo_u32_b32 v26, vcc_lo, 0
	s_lshl_b32 s7, s6, 2
	v_mbcnt_hi_u32_b32 v26, vcc_hi, v26
	s_add_i32 s7, s7, s15
	v_lshl_add_u32 v26, v26, 2, s7
	ds_write_b32 v26, v49
.LBB0_231:
	s_or_b64 exec, exec, s[0:1]
	s_bcnt1_i32_b64 s0, vcc
	s_add_i32 s6, s0, s6
	v_cmp_le_u32_e32 vcc, s81, v47
	v_cmp_ge_u32_e64 s[0:1], s80, v47
	s_and_b64 vcc, vcc, s[0:1]
	s_and_saveexec_b64 s[0:1], vcc
	v_mbcnt_lo_u32_b32 v26, vcc_lo, 0
	s_lshl_b32 s7, s6, 2
	v_mbcnt_hi_u32_b32 v26, vcc_hi, v26
	s_add_i32 s7, s7, s15
	v_lshl_add_u32 v26, v26, 2, s7
	ds_write_b32 v26, v47
.LBB0_233:
	s_or_b64 exec, exec, s[0:1]
	s_bcnt1_i32_b64 s0, vcc
	s_add_i32 s6, s6, s0
	v_cmp_le_u32_e32 vcc, s81, v46
	v_cmp_ge_u32_e64 s[0:1], s80, v46
	s_and_b64 vcc, vcc, s[0:1]
	s_and_saveexec_b64 s[0:1], vcc
	v_mbcnt_lo_u32_b32 v26, vcc_lo, 0
	s_lshl_b32 s7, s6, 2
	v_mbcnt_hi_u32_b32 v26, vcc_hi, v26
	s_add_i32 s7, s7, s15
	v_lshl_add_u32 v26, v26, 2, s7
	ds_write_b32 v26, v46
.LBB0_235:
	s_or_b64 exec, exec, s[0:1]
	s_bcnt1_i32_b64 s0, vcc
	s_add_i32 s6, s6, s0
	v_cmp_le_u32_e32 vcc, s81, v44
	v_cmp_ge_u32_e64 s[0:1], s80, v44
	s_and_b64 vcc, vcc, s[0:1]
	s_and_saveexec_b64 s[0:1], vcc
	v_mbcnt_lo_u32_b32 v26, vcc_lo, 0
	s_lshl_b32 s7, s6, 2
	v_mbcnt_hi_u32_b32 v26, vcc_hi, v26
	s_add_i32 s7, s7, s15
	v_lshl_add_u32 v26, v26, 2, s7
	ds_write_b32 v26, v44
.LBB0_237:
	s_or_b64 exec, exec, s[0:1]
	s_bcnt1_i32_b64 s0, vcc
	s_add_i32 s6, s6, s0
	v_cmp_le_u32_e32 vcc, s81, v43
	v_cmp_ge_u32_e64 s[0:1], s80, v43
	s_and_b64 vcc, vcc, s[0:1]
	s_and_saveexec_b64 s[0:1], vcc
	v_mbcnt_lo_u32_b32 v26, vcc_lo, 0
	s_lshl_b32 s7, s6, 2
	v_mbcnt_hi_u32_b32 v26, vcc_hi, v26
	s_add_i32 s7, s7, s15
	v_lshl_add_u32 v26, v26, 2, s7
	ds_write_b32 v26, v43
.LBB0_239:
	s_or_b64 exec, exec, s[0:1]
	s_bcnt1_i32_b64 s0, vcc
	s_add_i32 s6, s6, s0
	v_cmp_le_u32_e32 vcc, s81, v41
	v_cmp_ge_u32_e64 s[0:1], s80, v41
	s_and_b64 vcc, vcc, s[0:1]
	s_and_saveexec_b64 s[0:1], vcc
	v_mbcnt_lo_u32_b32 v26, vcc_lo, 0
	s_lshl_b32 s7, s6, 2
	v_mbcnt_hi_u32_b32 v26, vcc_hi, v26
	s_add_i32 s7, s7, s15
	v_lshl_add_u32 v26, v26, 2, s7
	ds_write_b32 v26, v41
.LBB0_241:
	s_or_b64 exec, exec, s[0:1]
	s_bcnt1_i32_b64 s0, vcc
	s_add_i32 s6, s6, s0
	v_cmp_le_u32_e32 vcc, s81, v48
	v_cmp_ge_u32_e64 s[0:1], s80, v48
	s_and_b64 vcc, vcc, s[0:1]
	s_and_saveexec_b64 s[0:1], vcc
	v_mbcnt_lo_u32_b32 v26, vcc_lo, 0
	s_lshl_b32 s7, s6, 2
	v_mbcnt_hi_u32_b32 v26, vcc_hi, v26
	s_add_i32 s7, s7, s15
	v_lshl_add_u32 v26, v26, 2, s7
	ds_write_b32 v26, v48
.LBB0_243:
	s_or_b64 exec, exec, s[0:1]
	s_bcnt1_i32_b64 s0, vcc
	s_add_i32 s6, s6, s0
	v_cmp_le_u32_e32 vcc, s81, v45
	v_cmp_ge_u32_e64 s[0:1], s80, v45
	s_and_b64 vcc, vcc, s[0:1]
	s_and_saveexec_b64 s[0:1], vcc
	v_mbcnt_lo_u32_b32 v26, vcc_lo, 0
	s_lshl_b32 s7, s6, 2
	v_mbcnt_hi_u32_b32 v26, vcc_hi, v26
	s_add_i32 s7, s7, s15
	v_lshl_add_u32 v26, v26, 2, s7
	ds_write_b32 v26, v45
.LBB0_245:
	s_or_b64 exec, exec, s[0:1]
	s_bcnt1_i32_b64 s0, vcc
	s_add_i32 s6, s6, s0
	v_cmp_le_u32_e32 vcc, s81, v42
	v_cmp_ge_u32_e64 s[0:1], s80, v42
	s_and_b64 vcc, vcc, s[0:1]
	s_and_saveexec_b64 s[0:1], vcc
	v_mbcnt_lo_u32_b32 v26, vcc_lo, 0
	s_lshl_b32 s7, s6, 2
	v_mbcnt_hi_u32_b32 v26, vcc_hi, v26
	s_add_i32 s7, s7, s15
	v_lshl_add_u32 v26, v26, 2, s7
	ds_write_b32 v26, v42
.LBB0_247:
	s_or_b64 exec, exec, s[0:1]
	s_bcnt1_i32_b64 s0, vcc
	s_add_i32 s6, s6, s0
	v_cmp_le_u32_e32 vcc, s81, v40
	v_cmp_ge_u32_e64 s[0:1], s80, v40
	s_and_b64 vcc, vcc, s[0:1]
	s_and_saveexec_b64 s[0:1], vcc
	v_mbcnt_lo_u32_b32 v26, vcc_lo, 0
	s_lshl_b32 s7, s6, 2
	v_mbcnt_hi_u32_b32 v26, vcc_hi, v26
	s_add_i32 s7, s7, s15
	v_lshl_add_u32 v26, v26, 2, s7
	ds_write_b32 v26, v40
.LBB0_249:
	s_or_b64 exec, exec, s[0:1]
	s_bcnt1_i32_b64 s0, vcc
	s_add_i32 s6, s6, s0
	v_cmp_le_u32_e32 vcc, s81, v38
	v_cmp_ge_u32_e64 s[0:1], s80, v38
	s_and_b64 vcc, vcc, s[0:1]
	s_and_saveexec_b64 s[0:1], vcc
	v_mbcnt_lo_u32_b32 v26, vcc_lo, 0
	s_lshl_b32 s7, s6, 2
	v_mbcnt_hi_u32_b32 v26, vcc_hi, v26
	s_add_i32 s7, s7, s15
	v_lshl_add_u32 v26, v26, 2, s7
	ds_write_b32 v26, v38
.LBB0_251:
	s_or_b64 exec, exec, s[0:1]
	s_bcnt1_i32_b64 s0, vcc
	s_add_i32 s6, s6, s0
	v_cmp_le_u32_e32 vcc, s81, v36
	v_cmp_ge_u32_e64 s[0:1], s80, v36
	s_and_b64 vcc, vcc, s[0:1]
	s_and_saveexec_b64 s[0:1], vcc
	v_mbcnt_lo_u32_b32 v26, vcc_lo, 0
	s_lshl_b32 s7, s6, 2
	v_mbcnt_hi_u32_b32 v26, vcc_hi, v26
	s_add_i32 s7, s7, s15
	v_lshl_add_u32 v26, v26, 2, s7
	ds_write_b32 v26, v36
.LBB0_253:
	s_or_b64 exec, exec, s[0:1]
	s_bcnt1_i32_b64 s0, vcc
	s_add_i32 s6, s6, s0
	v_cmp_le_u32_e32 vcc, s81, v35
	v_cmp_ge_u32_e64 s[0:1], s80, v35
	s_and_b64 vcc, vcc, s[0:1]
	s_and_saveexec_b64 s[0:1], vcc
	v_mbcnt_lo_u32_b32 v26, vcc_lo, 0
	s_lshl_b32 s7, s6, 2
	v_mbcnt_hi_u32_b32 v26, vcc_hi, v26
	s_add_i32 s7, s7, s15
	v_lshl_add_u32 v26, v26, 2, s7
	ds_write_b32 v26, v35
.LBB0_255:
	s_or_b64 exec, exec, s[0:1]
	s_bcnt1_i32_b64 s0, vcc
	s_add_i32 s6, s6, s0
	v_cmp_le_u32_e32 vcc, s81, v33
	v_cmp_ge_u32_e64 s[0:1], s80, v33
	s_and_b64 vcc, vcc, s[0:1]
	s_and_saveexec_b64 s[0:1], vcc
	v_mbcnt_lo_u32_b32 v26, vcc_lo, 0
	s_lshl_b32 s7, s6, 2
	v_mbcnt_hi_u32_b32 v26, vcc_hi, v26
	s_add_i32 s7, s7, s15
	v_lshl_add_u32 v26, v26, 2, s7
	ds_write_b32 v26, v33
; template <int NR>
; DI u64 select_wave(float* scw, int nreg, int lane) {
;     ...
;   if (!exact && lo < hi) {
;     unsigned* cand = reinterpret_cast<unsigned*>(scw);
;     int base = 0;
; #pragma unroll
;     for (int r = 0; r < NR; ++r) {
;       const bool pred = (key[r] >= lo) && (key[r] <= hi);
;       const u64 bal = __builtin_amdgcn_ballot_w64(pred);
;       const int pos = base + __builtin_amdgcn_mbcnt_hi((unsigned)(bal >> 32), __builtin_amdgcn_mbcnt_lo((unsigned)bal, 0u));
;       if (pred) cand[pos] = key[r];
;       base += __builtin_popcountll(bal);
;     }
.LBB0_257:
	s_or_b64 exec, exec, s[0:1]
	s_bcnt1_i32_b64 s0, vcc
	s_add_i32 s6, s6, s0
	v_cmp_le_u32_e32 vcc, s81, v39
	v_cmp_ge_u32_e64 s[0:1], s80, v39
	s_and_b64 vcc, vcc, s[0:1]
	s_and_saveexec_b64 s[0:1], vcc
	v_mbcnt_lo_u32_b32 v26, vcc_lo, 0
	s_lshl_b32 s7, s6, 2
	v_mbcnt_hi_u32_b32 v26, vcc_hi, v26
	s_add_i32 s7, s7, s15
	v_lshl_add_u32 v26, v26, 2, s7
	ds_write_b32 v26, v39
.LBB0_259:
	s_or_b64 exec, exec, s[0:1]
	s_bcnt1_i32_b64 s0, vcc
	s_add_i32 s6, s6, s0
	v_cmp_le_u32_e32 vcc, s81, v37
	v_cmp_ge_u32_e64 s[0:1], s80, v37
	s_and_b64 vcc, vcc, s[0:1]
	s_and_saveexec_b64 s[0:1], vcc
	v_mbcnt_lo_u32_b32 v26, vcc_lo, 0
	s_lshl_b32 s7, s6, 2
	v_mbcnt_hi_u32_b32 v26, vcc_hi, v26
	s_add_i32 s7, s7, s15
	v_lshl_add_u32 v26, v26, 2, s7
	ds_write_b32 v26, v37
.LBB0_261:
	s_or_b64 exec, exec, s[0:1]
	s_bcnt1_i32_b64 s0, vcc
	s_add_i32 s6, s6, s0
	v_cmp_le_u32_e32 vcc, s81, v34
	v_cmp_ge_u32_e64 s[0:1], s80, v34
	s_and_b64 vcc, vcc, s[0:1]
	s_and_saveexec_b64 s[0:1], vcc
	v_mbcnt_lo_u32_b32 v26, vcc_lo, 0
	s_lshl_b32 s7, s6, 2
	v_mbcnt_hi_u32_b32 v26, vcc_hi, v26
	s_add_i32 s7, s7, s15
	v_lshl_add_u32 v26, v26, 2, s7
	ds_write_b32 v26, v34
.LBB0_263:
	s_or_b64 exec, exec, s[0:1]
	s_bcnt1_i32_b64 s0, vcc
	s_add_i32 s6, s6, s0
	v_cmp_le_u32_e32 vcc, s81, v32
	v_cmp_ge_u32_e64 s[0:1], s80, v32
	s_and_b64 vcc, vcc, s[0:1]
	s_and_saveexec_b64 s[0:1], vcc
	v_mbcnt_lo_u32_b32 v26, vcc_lo, 0
	s_lshl_b32 s7, s6, 2
	v_mbcnt_hi_u32_b32 v26, vcc_hi, v26
	s_add_i32 s7, s7, s15
	v_lshl_add_u32 v26, v26, 2, s7
	ds_write_b32 v26, v32
.LBB0_265:
	s_or_b64 exec, exec, s[0:1]
	s_bcnt1_i32_b64 s0, vcc
	s_add_i32 s6, s6, s0
	v_cmp_le_u32_e32 vcc, s81, v30
	v_cmp_ge_u32_e64 s[0:1], s80, v30
	s_and_b64 vcc, vcc, s[0:1]
	s_and_saveexec_b64 s[0:1], vcc
	v_mbcnt_lo_u32_b32 v26, vcc_lo, 0
	s_lshl_b32 s7, s6, 2
	v_mbcnt_hi_u32_b32 v26, vcc_hi, v26
	s_add_i32 s7, s7, s15
	v_lshl_add_u32 v26, v26, 2, s7
	ds_write_b32 v26, v30
.LBB0_267:
	s_or_b64 exec, exec, s[0:1]
	s_bcnt1_i32_b64 s0, vcc
	s_add_i32 s6, s6, s0
	v_cmp_le_u32_e32 vcc, s81, v28
	v_cmp_ge_u32_e64 s[0:1], s80, v28
	s_and_b64 vcc, vcc, s[0:1]
	s_and_saveexec_b64 s[0:1], vcc
	v_mbcnt_lo_u32_b32 v26, vcc_lo, 0
	s_lshl_b32 s7, s6, 2
	v_mbcnt_hi_u32_b32 v26, vcc_hi, v26
	s_add_i32 s7, s7, s15
	v_lshl_add_u32 v26, v26, 2, s7
	ds_write_b32 v26, v28
.LBB0_269:
	s_or_b64 exec, exec, s[0:1]
	s_bcnt1_i32_b64 s0, vcc
	s_add_i32 s6, s6, s0
	v_cmp_le_u32_e32 vcc, s81, v25
	v_cmp_ge_u32_e64 s[0:1], s80, v25
	s_and_b64 vcc, vcc, s[0:1]
	s_and_saveexec_b64 s[0:1], vcc
	v_mbcnt_lo_u32_b32 v26, vcc_lo, 0
	s_lshl_b32 s7, s6, 2
	v_mbcnt_hi_u32_b32 v26, vcc_hi, v26
	s_add_i32 s7, s7, s15
	v_lshl_add_u32 v26, v26, 2, s7
	ds_write_b32 v26, v25
.LBB0_271:
	s_or_b64 exec, exec, s[0:1]
	s_bcnt1_i32_b64 s0, vcc
	s_add_i32 s6, s6, s0
	v_cmp_le_u32_e32 vcc, s81, v23
	v_cmp_ge_u32_e64 s[0:1], s80, v23
	s_and_b64 vcc, vcc, s[0:1]
	s_and_saveexec_b64 s[0:1], vcc
	v_mbcnt_lo_u32_b32 v26, vcc_lo, 0
	s_lshl_b32 s7, s6, 2
	v_mbcnt_hi_u32_b32 v26, vcc_hi, v26
	s_add_i32 s7, s7, s15
	v_lshl_add_u32 v26, v26, 2, s7
	ds_write_b32 v26, v23
.LBB0_273:
	s_or_b64 exec, exec, s[0:1]
	s_bcnt1_i32_b64 s0, vcc
	s_add_i32 s6, s6, s0
	v_cmp_le_u32_e32 vcc, s81, v31
	v_cmp_ge_u32_e64 s[0:1], s80, v31
	s_and_b64 vcc, vcc, s[0:1]
	s_and_saveexec_b64 s[0:1], vcc
	v_mbcnt_lo_u32_b32 v26, vcc_lo, 0
	s_lshl_b32 s7, s6, 2
	v_mbcnt_hi_u32_b32 v26, vcc_hi, v26
	s_add_i32 s7, s7, s15
	v_lshl_add_u32 v26, v26, 2, s7
	ds_write_b32 v26, v31
.LBB0_275:
	s_or_b64 exec, exec, s[0:1]
	s_bcnt1_i32_b64 s0, vcc
	s_add_i32 s6, s6, s0
	v_cmp_le_u32_e32 vcc, s81, v29
	v_cmp_ge_u32_e64 s[0:1], s80, v29
	s_and_b64 vcc, vcc, s[0:1]
	s_and_saveexec_b64 s[0:1], vcc
	v_mbcnt_lo_u32_b32 v26, vcc_lo, 0
	s_lshl_b32 s7, s6, 2
	v_mbcnt_hi_u32_b32 v26, vcc_hi, v26
	s_add_i32 s7, s7, s15
	v_lshl_add_u32 v26, v26, 2, s7
	ds_write_b32 v26, v29
.LBB0_277:
	s_or_b64 exec, exec, s[0:1]
	s_bcnt1_i32_b64 s0, vcc
	s_add_i32 s6, s6, s0
	v_cmp_le_u32_e32 vcc, s81, v24
	v_cmp_ge_u32_e64 s[0:1], s80, v24
	s_and_b64 vcc, vcc, s[0:1]
	s_and_saveexec_b64 s[0:1], vcc
	v_mbcnt_lo_u32_b32 v26, vcc_lo, 0
	s_lshl_b32 s7, s6, 2
	v_mbcnt_hi_u32_b32 v26, vcc_hi, v26
	s_add_i32 s7, s7, s15
	v_lshl_add_u32 v26, v26, 2, s7
	ds_write_b32 v26, v24
.LBB0_279:
	s_or_b64 exec, exec, s[0:1]
	s_bcnt1_i32_b64 s0, vcc
	s_add_i32 s6, s6, s0
	v_cmp_le_u32_e32 vcc, s81, v22
	v_cmp_ge_u32_e64 s[0:1], s80, v22
	s_and_b64 vcc, vcc, s[0:1]
	s_and_saveexec_b64 s[0:1], vcc
	v_mbcnt_lo_u32_b32 v26, vcc_lo, 0
	s_lshl_b32 s7, s6, 2
	v_mbcnt_hi_u32_b32 v26, vcc_hi, v26
	s_add_i32 s7, s7, s15
	v_lshl_add_u32 v26, v26, 2, s7
	ds_write_b32 v26, v22
.LBB0_281:
	s_or_b64 exec, exec, s[0:1]
	s_bcnt1_i32_b64 s0, vcc
	s_add_i32 s6, s6, s0
	v_cmp_le_u32_e32 vcc, s81, v21
	v_cmp_ge_u32_e64 s[0:1], s80, v21
	s_and_b64 vcc, vcc, s[0:1]
	s_and_saveexec_b64 s[0:1], vcc
	v_mbcnt_lo_u32_b32 v26, vcc_lo, 0
	s_lshl_b32 s7, s6, 2
	v_mbcnt_hi_u32_b32 v26, vcc_hi, v26
	s_add_i32 s7, s7, s15
	v_lshl_add_u32 v26, v26, 2, s7
	ds_write_b32 v26, v21
.LBB0_283:
	s_or_b64 exec, exec, s[0:1]
	s_bcnt1_i32_b64 s0, vcc
	s_add_i32 s6, s6, s0
	v_cmp_le_u32_e32 vcc, s81, v19
	v_cmp_ge_u32_e64 s[0:1], s80, v19
	s_and_b64 vcc, vcc, s[0:1]
	s_and_saveexec_b64 s[0:1], vcc
	v_mbcnt_lo_u32_b32 v26, vcc_lo, 0
	s_lshl_b32 s7, s6, 2
	v_mbcnt_hi_u32_b32 v26, vcc_hi, v26
	s_add_i32 s7, s7, s15
	v_lshl_add_u32 v26, v26, 2, s7
	ds_write_b32 v26, v19
.LBB0_285:
	s_or_b64 exec, exec, s[0:1]
	s_bcnt1_i32_b64 s0, vcc
	s_add_i32 s6, s6, s0
	v_cmp_le_u32_e32 vcc, s81, v20
	v_cmp_ge_u32_e64 s[0:1], s80, v20
	s_and_b64 vcc, vcc, s[0:1]
	s_and_saveexec_b64 s[0:1], vcc
	v_mbcnt_lo_u32_b32 v26, vcc_lo, 0
	s_lshl_b32 s7, s6, 2
	v_mbcnt_hi_u32_b32 v26, vcc_hi, v26
	s_add_i32 s7, s7, s15
	v_lshl_add_u32 v26, v26, 2, s7
	ds_write_b32 v26, v20
; template <int NR>
; DI u64 select_wave(float* scw, int nreg, int lane) {
;     ...
;   if (!exact && lo < hi) {
;     unsigned* cand = reinterpret_cast<unsigned*>(scw);
;     int base = 0;
; #pragma unroll
;     for (int r = 0; r < NR; ++r) {
;       const bool pred = (key[r] >= lo) && (key[r] <= hi);
;       const u64 bal = __builtin_amdgcn_ballot_w64(pred);
;       const int pos = base + __builtin_amdgcn_mbcnt_hi((unsigned)(bal >> 32), __builtin_amdgcn_mbcnt_lo((unsigned)bal, 0u));
;       if (pred) cand[pos] = key[r];
;       base += __builtin_popcountll(bal);
;     }
.LBB0_287:
	s_or_b64 exec, exec, s[0:1]
	s_bcnt1_i32_b64 s0, vcc
	s_add_i32 s6, s6, s0
	v_cmp_le_u32_e32 vcc, s81, v18
	v_cmp_ge_u32_e64 s[0:1], s80, v18
	s_and_b64 vcc, vcc, s[0:1]
	s_and_saveexec_b64 s[0:1], vcc
	v_mbcnt_lo_u32_b32 v26, vcc_lo, 0
	s_lshl_b32 s7, s6, 2
	v_mbcnt_hi_u32_b32 v26, vcc_hi, v26
	s_add_i32 s7, s7, s15
	v_lshl_add_u32 v26, v26, 2, s7
	ds_write_b32 v26, v18
.LBB0_289:
	s_or_b64 exec, exec, s[0:1]
	s_bcnt1_i32_b64 s0, vcc
	s_add_i32 s6, s6, s0
	v_cmp_le_u32_e32 vcc, s81, v17
	v_cmp_ge_u32_e64 s[0:1], s80, v17
	s_and_b64 vcc, vcc, s[0:1]
	s_and_saveexec_b64 s[0:1], vcc
	v_mbcnt_lo_u32_b32 v26, vcc_lo, 0
	s_lshl_b32 s7, s6, 2
	v_mbcnt_hi_u32_b32 v26, vcc_hi, v26
	s_add_i32 s7, s7, s15
	v_lshl_add_u32 v26, v26, 2, s7
	ds_write_b32 v26, v17
.LBB0_291:
	s_or_b64 exec, exec, s[0:1]
	s_bcnt1_i32_b64 s0, vcc
	s_add_i32 s6, s6, s0
	v_cmp_le_u32_e32 vcc, s81, v16
	v_cmp_ge_u32_e64 s[0:1], s80, v16
	s_and_b64 vcc, vcc, s[0:1]
	s_and_saveexec_b64 s[0:1], vcc
	v_mbcnt_lo_u32_b32 v26, vcc_lo, 0
	s_lshl_b32 s7, s6, 2
	v_mbcnt_hi_u32_b32 v26, vcc_hi, v26
	s_add_i32 s7, s7, s15
	v_lshl_add_u32 v26, v26, 2, s7
	ds_write_b32 v26, v16
.LBB0_293:
	s_or_b64 exec, exec, s[0:1]
	s_bcnt1_i32_b64 s0, vcc
	s_add_i32 s6, s6, s0
	v_cmp_le_u32_e32 vcc, s81, v51
	v_cmp_ge_u32_e64 s[0:1], s80, v51
	s_and_b64 vcc, vcc, s[0:1]
	s_and_saveexec_b64 s[0:1], vcc
	v_mbcnt_lo_u32_b32 v26, vcc_lo, 0
	s_lshl_b32 s7, s6, 2
	v_mbcnt_hi_u32_b32 v26, vcc_hi, v26
	s_add_i32 s7, s7, s15
	v_lshl_add_u32 v26, v26, 2, s7
	ds_write_b32 v26, v51
.LBB0_295:
	s_or_b64 exec, exec, s[0:1]
	s_bcnt1_i32_b64 s0, vcc
	s_add_i32 s6, s6, s0
	v_cmp_le_u32_e32 vcc, s81, v54
	v_cmp_ge_u32_e64 s[0:1], s80, v54
	s_and_b64 vcc, vcc, s[0:1]
	s_and_saveexec_b64 s[0:1], vcc
	v_mbcnt_lo_u32_b32 v26, vcc_lo, 0
	s_lshl_b32 s7, s6, 2
	v_mbcnt_hi_u32_b32 v26, vcc_hi, v26
	s_add_i32 s7, s7, s15
	v_lshl_add_u32 v26, v26, 2, s7
	ds_write_b32 v26, v54
.LBB0_297:
	s_or_b64 exec, exec, s[0:1]
	s_bcnt1_i32_b64 s0, vcc
	s_add_i32 s6, s6, s0
	v_cmp_le_u32_e32 vcc, s81, v3
	v_cmp_ge_u32_e64 s[0:1], s80, v3
	s_and_b64 vcc, vcc, s[0:1]
	s_and_saveexec_b64 s[0:1], vcc
	v_mbcnt_lo_u32_b32 v26, vcc_lo, 0
	s_lshl_b32 s7, s6, 2
	v_mbcnt_hi_u32_b32 v26, vcc_hi, v26
	s_add_i32 s7, s7, s15
	v_lshl_add_u32 v26, v26, 2, s7
	ds_write_b32 v26, v3
.LBB0_299:
	s_or_b64 exec, exec, s[0:1]
	s_bcnt1_i32_b64 s0, vcc
	s_add_i32 s6, s6, s0
	v_cmp_le_u32_e32 vcc, s81, v2
	v_cmp_ge_u32_e64 s[0:1], s80, v2
	s_and_b64 vcc, vcc, s[0:1]
	s_and_saveexec_b64 s[0:1], vcc
	v_mbcnt_lo_u32_b32 v26, vcc_lo, 0
	s_lshl_b32 s7, s6, 2
	v_mbcnt_hi_u32_b32 v26, vcc_hi, v26
	s_add_i32 s7, s7, s15
	v_lshl_add_u32 v26, v26, 2, s7
	ds_write_b32 v26, v2
.LBB0_301:
	s_or_b64 exec, exec, s[0:1]
	s_bcnt1_i32_b64 s0, vcc
	s_add_i32 s6, s6, s0
	v_cmp_le_u32_e32 vcc, s81, v5
	v_cmp_ge_u32_e64 s[0:1], s80, v5
	s_and_b64 vcc, vcc, s[0:1]
	s_and_saveexec_b64 s[0:1], vcc
	v_mbcnt_lo_u32_b32 v26, vcc_lo, 0
	s_lshl_b32 s7, s6, 2
	v_mbcnt_hi_u32_b32 v26, vcc_hi, v26
	s_add_i32 s7, s7, s15
	v_lshl_add_u32 v26, v26, 2, s7
	ds_write_b32 v26, v5
.LBB0_303:
	s_or_b64 exec, exec, s[0:1]
	s_bcnt1_i32_b64 s0, vcc
	s_add_i32 s6, s6, s0
	v_cmp_le_u32_e32 vcc, s81, v4
	v_cmp_ge_u32_e64 s[0:1], s80, v4
	s_and_b64 vcc, vcc, s[0:1]
	s_and_saveexec_b64 s[0:1], vcc
	v_mbcnt_lo_u32_b32 v26, vcc_lo, 0
	s_lshl_b32 s7, s6, 2
	v_mbcnt_hi_u32_b32 v26, vcc_hi, v26
	s_add_i32 s7, s7, s15
	v_lshl_add_u32 v26, v26, 2, s7
	ds_write_b32 v26, v4
.LBB0_305:
	s_or_b64 exec, exec, s[0:1]
	s_bcnt1_i32_b64 s0, vcc
	s_add_i32 s6, s6, s0
	v_cmp_le_u32_e32 vcc, s81, v9
	v_cmp_ge_u32_e64 s[0:1], s80, v9
	s_and_b64 vcc, vcc, s[0:1]
	s_and_saveexec_b64 s[0:1], vcc
	v_mbcnt_lo_u32_b32 v26, vcc_lo, 0
	s_lshl_b32 s7, s6, 2
	v_mbcnt_hi_u32_b32 v26, vcc_hi, v26
	s_add_i32 s7, s7, s15
	v_lshl_add_u32 v26, v26, 2, s7
	ds_write_b32 v26, v9
.LBB0_307:
	s_or_b64 exec, exec, s[0:1]
	s_bcnt1_i32_b64 s0, vcc
	s_add_i32 s6, s6, s0
	v_cmp_le_u32_e32 vcc, s81, v8
	v_cmp_ge_u32_e64 s[0:1], s80, v8
	s_and_b64 vcc, vcc, s[0:1]
	s_and_saveexec_b64 s[0:1], vcc
	v_mbcnt_lo_u32_b32 v26, vcc_lo, 0
	s_lshl_b32 s7, s6, 2
	v_mbcnt_hi_u32_b32 v26, vcc_hi, v26
	s_add_i32 s7, s7, s15
	v_lshl_add_u32 v26, v26, 2, s7
	ds_write_b32 v26, v8
.LBB0_309:
	s_or_b64 exec, exec, s[0:1]
	s_bcnt1_i32_b64 s0, vcc
	s_add_i32 s6, s6, s0
	v_cmp_le_u32_e32 vcc, s81, v7
	v_cmp_ge_u32_e64 s[0:1], s80, v7
	s_and_b64 vcc, vcc, s[0:1]
	s_and_saveexec_b64 s[0:1], vcc
	v_mbcnt_lo_u32_b32 v26, vcc_lo, 0
	s_lshl_b32 s7, s6, 2
	v_mbcnt_hi_u32_b32 v26, vcc_hi, v26
	s_add_i32 s7, s7, s15
	v_lshl_add_u32 v26, v26, 2, s7
	ds_write_b32 v26, v7
.LBB0_311:
	s_or_b64 exec, exec, s[0:1]
	s_bcnt1_i32_b64 s0, vcc
	s_add_i32 s6, s6, s0
	v_cmp_le_u32_e32 vcc, s81, v6
	v_cmp_ge_u32_e64 s[0:1], s80, v6
	s_and_b64 vcc, vcc, s[0:1]
	s_and_saveexec_b64 s[0:1], vcc
	v_mbcnt_lo_u32_b32 v26, vcc_lo, 0
	s_lshl_b32 s7, s6, 2
	v_mbcnt_hi_u32_b32 v26, vcc_hi, v26
	s_add_i32 s7, s7, s15
	v_lshl_add_u32 v26, v26, 2, s7
	ds_write_b32 v26, v6
.LBB0_313:
	s_or_b64 exec, exec, s[0:1]
	s_bcnt1_i32_b64 s0, vcc
	s_add_i32 s6, s6, s0
	v_cmp_le_u32_e32 vcc, s81, v11
	v_cmp_ge_u32_e64 s[0:1], s80, v11
	s_and_b64 vcc, vcc, s[0:1]
	s_and_saveexec_b64 s[0:1], vcc
	v_mbcnt_lo_u32_b32 v26, vcc_lo, 0
	s_lshl_b32 s7, s6, 2
	v_mbcnt_hi_u32_b32 v26, vcc_hi, v26
	s_add_i32 s7, s7, s15
	v_lshl_add_u32 v26, v26, 2, s7
	ds_write_b32 v26, v11
.LBB0_315:
	s_or_b64 exec, exec, s[0:1]
	s_bcnt1_i32_b64 s0, vcc
	s_add_i32 s6, s6, s0
	v_cmp_le_u32_e32 vcc, s81, v10
	v_cmp_ge_u32_e64 s[0:1], s80, v10
	s_and_b64 vcc, vcc, s[0:1]
	s_and_saveexec_b64 s[0:1], vcc
	v_mbcnt_lo_u32_b32 v26, vcc_lo, 0
	s_lshl_b32 s7, s6, 2
	v_mbcnt_hi_u32_b32 v26, vcc_hi, v26
	s_add_i32 s7, s7, s15
	v_lshl_add_u32 v26, v26, 2, s7
	ds_write_b32 v26, v10
; template <int NR>
; DI u64 select_wave(float* scw, int nreg, int lane) {
;     ...
;   if (!exact && lo < hi) {
;     unsigned* cand = reinterpret_cast<unsigned*>(scw);
;     int base = 0;
; #pragma unroll
;     for (int r = 0; r < NR; ++r) {
;       const bool pred = (key[r] >= lo) && (key[r] <= hi);
;       const u64 bal = __builtin_amdgcn_ballot_w64(pred);
;       const int pos = base + __builtin_amdgcn_mbcnt_hi((unsigned)(bal >> 32), __builtin_amdgcn_mbcnt_lo((unsigned)bal, 0u));
;       if (pred) cand[pos] = key[r];
;       base += __builtin_popcountll(bal);
;     }
.LBB0_317:
	s_or_b64 exec, exec, s[0:1]
	s_bcnt1_i32_b64 s0, vcc
	s_add_i32 s6, s6, s0
	v_cmp_le_u32_e32 vcc, s81, v13
	v_cmp_ge_u32_e64 s[0:1], s80, v13
	s_and_b64 vcc, vcc, s[0:1]
	s_and_saveexec_b64 s[0:1], vcc
	v_mbcnt_lo_u32_b32 v26, vcc_lo, 0
	s_lshl_b32 s7, s6, 2
	v_mbcnt_hi_u32_b32 v26, vcc_hi, v26
	s_add_i32 s7, s7, s15
	v_lshl_add_u32 v26, v26, 2, s7
	ds_write_b32 v26, v13
.LBB0_319:
	s_or_b64 exec, exec, s[0:1]
	s_bcnt1_i32_b64 s0, vcc
	s_add_i32 s6, s6, s0
	v_cmp_le_u32_e32 vcc, s81, v12
	v_cmp_ge_u32_e64 s[0:1], s80, v12
	s_and_b64 vcc, vcc, s[0:1]
	s_and_saveexec_b64 s[0:1], vcc
	v_mbcnt_lo_u32_b32 v26, vcc_lo, 0
	s_lshl_b32 s7, s6, 2
	v_mbcnt_hi_u32_b32 v26, vcc_hi, v26
	s_add_i32 s7, s7, s15
	v_lshl_add_u32 v26, v26, 2, s7
	ds_write_b32 v26, v12
.LBB0_321:
	s_or_b64 exec, exec, s[0:1]
	s_bcnt1_i32_b64 s0, vcc
	s_add_i32 s6, s6, s0
	v_cmp_le_u32_e32 vcc, s81, v15
	v_cmp_ge_u32_e64 s[0:1], s80, v15
	s_and_b64 vcc, vcc, s[0:1]
	s_and_saveexec_b64 s[0:1], vcc
	v_mbcnt_lo_u32_b32 v26, vcc_lo, 0
	s_lshl_b32 s7, s6, 2
	v_mbcnt_hi_u32_b32 v26, vcc_hi, v26
	s_add_i32 s7, s7, s15
	v_lshl_add_u32 v26, v26, 2, s7
	ds_write_b32 v26, v15
.LBB0_323:
	s_or_b64 exec, exec, s[0:1]
	s_bcnt1_i32_b64 s0, vcc
	s_add_i32 s6, s6, s0
	v_cmp_le_u32_e32 vcc, s81, v14
	v_cmp_ge_u32_e64 s[0:1], s80, v14
	s_and_b64 vcc, vcc, s[0:1]
	s_and_saveexec_b64 s[0:1], vcc
	v_mbcnt_lo_u32_b32 v26, vcc_lo, 0
	s_lshl_b32 s7, s6, 2
	v_mbcnt_hi_u32_b32 v26, vcc_hi, v26
	s_add_i32 s7, s7, s15
	v_lshl_add_u32 v26, v26, 2, s7
	ds_write_b32 v26, v14
.LBB0_325:
	s_or_b64 exec, exec, s[0:1]
	s_bcnt1_i32_b64 s0, vcc
	s_add_i32 s6, s6, s0
	v_cmp_le_u32_e32 vcc, s81, v56
	v_cmp_ge_u32_e64 s[0:1], s80, v56
	s_and_b64 vcc, vcc, s[0:1]
	s_and_saveexec_b64 s[0:1], vcc
	v_mbcnt_lo_u32_b32 v26, vcc_lo, 0
	s_lshl_b32 s7, s6, 2
	v_mbcnt_hi_u32_b32 v26, vcc_hi, v26
	s_add_i32 s7, s7, s15
	v_lshl_add_u32 v26, v26, 2, s7
	ds_write_b32 v26, v56
.LBB0_327:
	s_or_b64 exec, exec, s[0:1]
	s_bcnt1_i32_b64 s0, vcc
	s_add_i32 s6, s6, s0
	v_cmp_le_u32_e32 vcc, s81, v57
	v_cmp_ge_u32_e64 s[0:1], s80, v57
	s_and_b64 vcc, vcc, s[0:1]
	s_and_saveexec_b64 s[0:1], vcc
	v_mbcnt_lo_u32_b32 v26, vcc_lo, 0
	s_lshl_b32 s7, s6, 2
	v_mbcnt_hi_u32_b32 v26, vcc_hi, v26
	s_add_i32 s7, s7, s15
	v_lshl_add_u32 v26, v26, 2, s7
	ds_write_b32 v26, v57
.LBB0_329:
	s_or_b64 exec, exec, s[0:1]
	s_bcnt1_i32_b64 s0, vcc
	s_add_i32 s6, s6, s0
	v_cmp_le_u32_e32 vcc, s81, v55
	v_cmp_ge_u32_e64 s[0:1], s80, v55
	s_and_b64 vcc, vcc, s[0:1]
	s_and_saveexec_b64 s[0:1], vcc
	v_mbcnt_lo_u32_b32 v26, vcc_lo, 0
	s_lshl_b32 s7, s6, 2
	v_mbcnt_hi_u32_b32 v26, vcc_hi, v26
	s_add_i32 s7, s7, s15
	v_lshl_add_u32 v26, v26, 2, s7
	ds_write_b32 v26, v55
.LBB0_331:
	s_or_b64 exec, exec, s[0:1]
	s_bcnt1_i32_b64 s0, vcc
	s_add_i32 s6, s6, s0
	v_cmp_le_u32_e32 vcc, s81, v59
	v_cmp_ge_u32_e64 s[0:1], s80, v59
	s_and_b64 vcc, vcc, s[0:1]
	s_and_saveexec_b64 s[0:1], vcc
	v_mbcnt_lo_u32_b32 v26, vcc_lo, 0
	s_lshl_b32 s7, s6, 2
	v_mbcnt_hi_u32_b32 v26, vcc_hi, v26
	s_add_i32 s7, s7, s15
	v_lshl_add_u32 v26, v26, 2, s7
	ds_write_b32 v26, v59
.LBB0_333:
	s_or_b64 exec, exec, s[0:1]
	s_bcnt1_i32_b64 s0, vcc
	s_add_i32 s6, s6, s0
	v_cmp_le_u32_e32 vcc, s81, v58
	v_cmp_ge_u32_e64 s[0:1], s80, v58
	s_and_b64 vcc, vcc, s[0:1]
	s_and_saveexec_b64 s[0:1], vcc
	v_mbcnt_lo_u32_b32 v26, vcc_lo, 0
	s_lshl_b32 s7, s6, 2
	v_mbcnt_hi_u32_b32 v26, vcc_hi, v26
	s_add_i32 s7, s7, s15
	v_lshl_add_u32 v26, v26, 2, s7
	ds_write_b32 v26, v58
.LBB0_335:
	s_or_b64 exec, exec, s[0:1]
	s_bcnt1_i32_b64 s0, vcc
	s_add_i32 s6, s6, s0
	v_cmp_le_u32_e32 vcc, s81, v61
	v_cmp_ge_u32_e64 s[0:1], s80, v61
	s_and_b64 vcc, vcc, s[0:1]
	s_and_saveexec_b64 s[0:1], vcc
	v_mbcnt_lo_u32_b32 v26, vcc_lo, 0
	s_lshl_b32 s7, s6, 2
	v_mbcnt_hi_u32_b32 v26, vcc_hi, v26
	s_add_i32 s7, s7, s15
	v_lshl_add_u32 v26, v26, 2, s7
	ds_write_b32 v26, v61
.LBB0_337:
	s_or_b64 exec, exec, s[0:1]
	s_bcnt1_i32_b64 s0, vcc
	s_add_i32 s6, s6, s0
	v_cmp_le_u32_e32 vcc, s81, v60
	v_cmp_ge_u32_e64 s[0:1], s80, v60
	s_and_b64 vcc, vcc, s[0:1]
	s_and_saveexec_b64 s[0:1], vcc
	v_mbcnt_lo_u32_b32 v26, vcc_lo, 0
	s_lshl_b32 s7, s6, 2
	v_mbcnt_hi_u32_b32 v26, vcc_hi, v26
	s_add_i32 s7, s7, s15
	v_lshl_add_u32 v26, v26, 2, s7
	ds_write_b32 v26, v60
.LBB0_339:
	s_or_b64 exec, exec, s[0:1]
	s_bcnt1_i32_b64 s0, vcc
	s_add_i32 s6, s6, s0
	v_cmp_le_u32_e32 vcc, s81, v64
	v_cmp_ge_u32_e64 s[0:1], s80, v64
	s_and_b64 vcc, vcc, s[0:1]
	s_and_saveexec_b64 s[0:1], vcc
	v_mbcnt_lo_u32_b32 v26, vcc_lo, 0
	s_lshl_b32 s7, s6, 2
	v_mbcnt_hi_u32_b32 v26, vcc_hi, v26
	s_add_i32 s7, s7, s15
	v_lshl_add_u32 v26, v26, 2, s7
	ds_write_b32 v26, v64
.LBB0_341:
	s_or_b64 exec, exec, s[0:1]
	s_bcnt1_i32_b64 s0, vcc
	s_add_i32 s6, s6, s0
	v_cmp_le_u32_e32 vcc, s81, v62
	v_cmp_ge_u32_e64 s[0:1], s80, v62
	s_and_b64 vcc, vcc, s[0:1]
	s_and_saveexec_b64 s[0:1], vcc
	v_mbcnt_lo_u32_b32 v26, vcc_lo, 0
	s_lshl_b32 s7, s6, 2
	v_mbcnt_hi_u32_b32 v26, vcc_hi, v26
	s_add_i32 s7, s7, s15
	v_lshl_add_u32 v26, v26, 2, s7
	ds_write_b32 v26, v62
.LBB0_343:
	s_or_b64 exec, exec, s[0:1]
	s_bcnt1_i32_b64 s0, vcc
	s_add_i32 s6, s6, s0
	v_cmp_le_u32_e32 vcc, s81, v65
	v_cmp_ge_u32_e64 s[0:1], s80, v65
	s_and_b64 vcc, vcc, s[0:1]
	s_and_saveexec_b64 s[0:1], vcc
	v_mbcnt_lo_u32_b32 v26, vcc_lo, 0
	s_lshl_b32 s7, s6, 2
	v_mbcnt_hi_u32_b32 v26, vcc_hi, v26
	s_add_i32 s7, s7, s15
	v_lshl_add_u32 v26, v26, 2, s7
	ds_write_b32 v26, v65
.LBB0_345:
	s_or_b64 exec, exec, s[0:1]
	s_bcnt1_i32_b64 s0, vcc
	s_add_i32 s6, s6, s0
	v_cmp_le_u32_e32 vcc, s81, v63
	v_cmp_ge_u32_e64 s[0:1], s80, v63
	s_and_b64 vcc, vcc, s[0:1]
	s_and_saveexec_b64 s[0:1], vcc
	v_mbcnt_lo_u32_b32 v26, vcc_lo, 0
	s_lshl_b32 s7, s6, 2
	v_mbcnt_hi_u32_b32 v26, vcc_hi, v26
	s_add_i32 s7, s7, s15
	v_lshl_add_u32 v26, v26, 2, s7
	ds_write_b32 v26, v63
.LBB0_347:
	s_or_b64 exec, exec, s[0:1]
	s_bcnt1_i32_b64 s0, vcc
	s_add_i32 s6, s6, s0
	v_cmp_le_u32_e32 vcc, s81, v67
	v_cmp_ge_u32_e64 s[0:1], s80, v67
	s_and_b64 vcc, vcc, s[0:1]
	s_and_saveexec_b64 s[0:1], vcc
	v_mbcnt_lo_u32_b32 v26, vcc_lo, 0
	s_lshl_b32 s7, s6, 2
	v_mbcnt_hi_u32_b32 v26, vcc_hi, v26
	s_add_i32 s7, s7, s15
	v_lshl_add_u32 v26, v26, 2, s7
	ds_write_b32 v26, v67
.LBB0_349:
	s_or_b64 exec, exec, s[0:1]
	s_bcnt1_i32_b64 s0, vcc
	s_add_i32 s6, s6, s0
	v_cmp_le_u32_e32 vcc, s81, v66
	v_cmp_ge_u32_e64 s[0:1], s80, v66
	s_and_b64 vcc, vcc, s[0:1]
	s_and_saveexec_b64 s[0:1], vcc
	v_mbcnt_lo_u32_b32 v26, vcc_lo, 0
	s_lshl_b32 s7, s6, 2
	v_mbcnt_hi_u32_b32 v26, vcc_hi, v26
	s_add_i32 s7, s7, s15
	v_lshl_add_u32 v26, v26, 2, s7
	ds_write_b32 v26, v66
.LBB0_351:
	s_or_b64 exec, exec, s[0:1]
	s_bcnt1_i32_b64 s0, vcc
	s_add_i32 s6, s6, s0
	v_cmp_le_u32_e32 vcc, s81, v69
	v_cmp_ge_u32_e64 s[0:1], s80, v69
	s_and_b64 vcc, vcc, s[0:1]
	s_and_saveexec_b64 s[0:1], vcc
	v_mbcnt_lo_u32_b32 v26, vcc_lo, 0
	s_lshl_b32 s7, s6, 2
	v_mbcnt_hi_u32_b32 v26, vcc_hi, v26
	s_add_i32 s7, s7, s15
	v_lshl_add_u32 v26, v26, 2, s7
	ds_write_b32 v26, v69

; template <int NR>
; DI u64 select_wave(float* scw, int nreg, int lane) {
;     ...
;   if (!exact && lo < hi) {
;     unsigned* cand = reinterpret_cast<unsigned*>(scw);
;     int base = 0;
; #pragma unroll
;     for (int r = 0; r < NR; ++r) {
;       const bool pred = (key[r] >= lo) && (key[r] <= hi);
;       const u64 bal = __builtin_amdgcn_ballot_w64(pred);
;       const int pos = base + __builtin_amdgcn_mbcnt_hi((unsigned)(bal >> 32), __builtin_amdgcn_mbcnt_lo((unsigned)bal, 0u));
;       if (pred) cand[pos] = key[r];
;       base += __builtin_popcountll(bal);
;     }
.LBB0_384:
	s_mov_b64 s[2:3], -1
	s_and_b64 vcc, exec, s[0:1]
	s_cbranch_vccnz .LBB0_491
	s_cmp_ge_u32 s79, s78
	s_mov_b64 s[0:1], 0
	s_cbranch_scc1 .LBB0_489
	v_cmp_le_u32_e32 vcc, s79, v50
	v_cmp_ge_u32_e64 s[0:1], s78, v50
	s_and_b64 vcc, vcc, s[0:1]
	s_and_saveexec_b64 s[0:1], vcc
	v_mbcnt_lo_u32_b32 v26, vcc_lo, 0
	v_mbcnt_hi_u32_b32 v26, vcc_hi, v26
	v_lshl_add_u32 v26, v26, 2, s15
	ds_write_b32 v26, v50
	s_or_b64 exec, exec, s[0:1]
	s_bcnt1_i32_b64 s6, vcc
	v_cmp_le_u32_e32 vcc, s79, v49
	v_cmp_ge_u32_e64 s[0:1], s78, v49
	s_and_b64 vcc, vcc, s[0:1]
	s_and_saveexec_b64 s[0:1], vcc
	v_mbcnt_lo_u32_b32 v26, vcc_lo, 0
	s_lshl_b32 s7, s6, 2
	v_mbcnt_hi_u32_b32 v26, vcc_hi, v26
	s_add_i32 s7, s7, s15
	v_lshl_add_u32 v26, v26, 2, s7
	ds_write_b32 v26, v49
.LBB0_390:
	s_or_b64 exec, exec, s[0:1]
	s_bcnt1_i32_b64 s0, vcc
	s_add_i32 s6, s0, s6
	v_cmp_le_u32_e32 vcc, s79, v47
	v_cmp_ge_u32_e64 s[0:1], s78, v47
	s_and_b64 vcc, vcc, s[0:1]
	s_and_saveexec_b64 s[0:1], vcc
	v_mbcnt_lo_u32_b32 v26, vcc_lo, 0
	s_lshl_b32 s7, s6, 2
	v_mbcnt_hi_u32_b32 v26, vcc_hi, v26
	s_add_i32 s7, s7, s15
	v_lshl_add_u32 v26, v26, 2, s7
	ds_write_b32 v26, v47
.LBB0_392:
	s_or_b64 exec, exec, s[0:1]
	s_bcnt1_i32_b64 s0, vcc
	s_add_i32 s6, s6, s0
	v_cmp_le_u32_e32 vcc, s79, v46
	v_cmp_ge_u32_e64 s[0:1], s78, v46
	s_and_b64 vcc, vcc, s[0:1]
	s_and_saveexec_b64 s[0:1], vcc
	v_mbcnt_lo_u32_b32 v26, vcc_lo, 0
	s_lshl_b32 s7, s6, 2
	v_mbcnt_hi_u32_b32 v26, vcc_hi, v26
	s_add_i32 s7, s7, s15
	v_lshl_add_u32 v26, v26, 2, s7
	ds_write_b32 v26, v46
.LBB0_394:
	s_or_b64 exec, exec, s[0:1]
	s_bcnt1_i32_b64 s0, vcc
	s_add_i32 s6, s6, s0
	v_cmp_le_u32_e32 vcc, s79, v44
	v_cmp_ge_u32_e64 s[0:1], s78, v44
	s_and_b64 vcc, vcc, s[0:1]
	s_and_saveexec_b64 s[0:1], vcc
	v_mbcnt_lo_u32_b32 v26, vcc_lo, 0
	s_lshl_b32 s7, s6, 2
	v_mbcnt_hi_u32_b32 v26, vcc_hi, v26
	s_add_i32 s7, s7, s15
	v_lshl_add_u32 v26, v26, 2, s7
	ds_write_b32 v26, v44
.LBB0_396:
	s_or_b64 exec, exec, s[0:1]
	s_bcnt1_i32_b64 s0, vcc
	s_add_i32 s6, s6, s0
	v_cmp_le_u32_e32 vcc, s79, v43
	v_cmp_ge_u32_e64 s[0:1], s78, v43
	s_and_b64 vcc, vcc, s[0:1]
	s_and_saveexec_b64 s[0:1], vcc
	v_mbcnt_lo_u32_b32 v26, vcc_lo, 0
	s_lshl_b32 s7, s6, 2
	v_mbcnt_hi_u32_b32 v26, vcc_hi, v26
	s_add_i32 s7, s7, s15
	v_lshl_add_u32 v26, v26, 2, s7
	ds_write_b32 v26, v43
.LBB0_398:
	s_or_b64 exec, exec, s[0:1]
	s_bcnt1_i32_b64 s0, vcc
	s_add_i32 s6, s6, s0
	v_cmp_le_u32_e32 vcc, s79, v41
	v_cmp_ge_u32_e64 s[0:1], s78, v41
	s_and_b64 vcc, vcc, s[0:1]
	s_and_saveexec_b64 s[0:1], vcc
	v_mbcnt_lo_u32_b32 v26, vcc_lo, 0
	s_lshl_b32 s7, s6, 2
	v_mbcnt_hi_u32_b32 v26, vcc_hi, v26
	s_add_i32 s7, s7, s15
	v_lshl_add_u32 v26, v26, 2, s7
	ds_write_b32 v26, v41
.LBB0_400:
	s_or_b64 exec, exec, s[0:1]
	s_bcnt1_i32_b64 s0, vcc
	s_add_i32 s6, s6, s0
	v_cmp_le_u32_e32 vcc, s79, v48
	v_cmp_ge_u32_e64 s[0:1], s78, v48
	s_and_b64 vcc, vcc, s[0:1]
	s_and_saveexec_b64 s[0:1], vcc
	v_mbcnt_lo_u32_b32 v26, vcc_lo, 0
	s_lshl_b32 s7, s6, 2
	v_mbcnt_hi_u32_b32 v26, vcc_hi, v26
	s_add_i32 s7, s7, s15
	v_lshl_add_u32 v26, v26, 2, s7
	ds_write_b32 v26, v48
.LBB0_402:
	s_or_b64 exec, exec, s[0:1]
	s_bcnt1_i32_b64 s0, vcc
	s_add_i32 s6, s6, s0
	v_cmp_le_u32_e32 vcc, s79, v45
	v_cmp_ge_u32_e64 s[0:1], s78, v45
	s_and_b64 vcc, vcc, s[0:1]
	s_and_saveexec_b64 s[0:1], vcc
	v_mbcnt_lo_u32_b32 v26, vcc_lo, 0
	s_lshl_b32 s7, s6, 2
	v_mbcnt_hi_u32_b32 v26, vcc_hi, v26
	s_add_i32 s7, s7, s15
	v_lshl_add_u32 v26, v26, 2, s7
	ds_write_b32 v26, v45
.LBB0_404:
	s_or_b64 exec, exec, s[0:1]
	s_bcnt1_i32_b64 s0, vcc
	s_add_i32 s6, s6, s0
	v_cmp_le_u32_e32 vcc, s79, v42
	v_cmp_ge_u32_e64 s[0:1], s78, v42
	s_and_b64 vcc, vcc, s[0:1]
	s_and_saveexec_b64 s[0:1], vcc
	v_mbcnt_lo_u32_b32 v26, vcc_lo, 0
	s_lshl_b32 s7, s6, 2
	v_mbcnt_hi_u32_b32 v26, vcc_hi, v26
	s_add_i32 s7, s7, s15
	v_lshl_add_u32 v26, v26, 2, s7
	ds_write_b32 v26, v42
.LBB0_406:
	s_or_b64 exec, exec, s[0:1]
	s_bcnt1_i32_b64 s0, vcc
	s_add_i32 s6, s6, s0
	v_cmp_le_u32_e32 vcc, s79, v40
	v_cmp_ge_u32_e64 s[0:1], s78, v40
	s_and_b64 vcc, vcc, s[0:1]
	s_and_saveexec_b64 s[0:1], vcc
	v_mbcnt_lo_u32_b32 v26, vcc_lo, 0
	s_lshl_b32 s7, s6, 2
	v_mbcnt_hi_u32_b32 v26, vcc_hi, v26
	s_add_i32 s7, s7, s15
	v_lshl_add_u32 v26, v26, 2, s7
	ds_write_b32 v26, v40
.LBB0_408:
	s_or_b64 exec, exec, s[0:1]
	s_bcnt1_i32_b64 s0, vcc
	s_add_i32 s6, s6, s0
	v_cmp_le_u32_e32 vcc, s79, v38
	v_cmp_ge_u32_e64 s[0:1], s78, v38
	s_and_b64 vcc, vcc, s[0:1]
	s_and_saveexec_b64 s[0:1], vcc
	v_mbcnt_lo_u32_b32 v26, vcc_lo, 0
	s_lshl_b32 s7, s6, 2
	v_mbcnt_hi_u32_b32 v26, vcc_hi, v26
	s_add_i32 s7, s7, s15
	v_lshl_add_u32 v26, v26, 2, s7
	ds_write_b32 v26, v38
.LBB0_410:
	s_or_b64 exec, exec, s[0:1]
	s_bcnt1_i32_b64 s0, vcc
	s_add_i32 s6, s6, s0
	v_cmp_le_u32_e32 vcc, s79, v36
	v_cmp_ge_u32_e64 s[0:1], s78, v36
	s_and_b64 vcc, vcc, s[0:1]
	s_and_saveexec_b64 s[0:1], vcc
	v_mbcnt_lo_u32_b32 v26, vcc_lo, 0
	s_lshl_b32 s7, s6, 2
	v_mbcnt_hi_u32_b32 v26, vcc_hi, v26
	s_add_i32 s7, s7, s15
	v_lshl_add_u32 v26, v26, 2, s7
	ds_write_b32 v26, v36
.LBB0_412:
	s_or_b64 exec, exec, s[0:1]
	s_bcnt1_i32_b64 s0, vcc
	s_add_i32 s6, s6, s0
	v_cmp_le_u32_e32 vcc, s79, v35
	v_cmp_ge_u32_e64 s[0:1], s78, v35
	s_and_b64 vcc, vcc, s[0:1]
	s_and_saveexec_b64 s[0:1], vcc
	v_mbcnt_lo_u32_b32 v26, vcc_lo, 0
	s_lshl_b32 s7, s6, 2
	v_mbcnt_hi_u32_b32 v26, vcc_hi, v26
	s_add_i32 s7, s7, s15
	v_lshl_add_u32 v26, v26, 2, s7
	ds_write_b32 v26, v35
.LBB0_414:
	s_or_b64 exec, exec, s[0:1]
	s_bcnt1_i32_b64 s0, vcc
	s_add_i32 s6, s6, s0
	v_cmp_le_u32_e32 vcc, s79, v33
	v_cmp_ge_u32_e64 s[0:1], s78, v33
	s_and_b64 vcc, vcc, s[0:1]
	s_and_saveexec_b64 s[0:1], vcc
	v_mbcnt_lo_u32_b32 v26, vcc_lo, 0
	s_lshl_b32 s7, s6, 2
	v_mbcnt_hi_u32_b32 v26, vcc_hi, v26
	s_add_i32 s7, s7, s15
	v_lshl_add_u32 v26, v26, 2, s7
	ds_write_b32 v26, v33
; template <int NR>
; DI u64 select_wave(float* scw, int nreg, int lane) {
;     ...
;   if (!exact && lo < hi) {
;     unsigned* cand = reinterpret_cast<unsigned*>(scw);
;     int base = 0;
; #pragma unroll
;     for (int r = 0; r < NR; ++r) {
;       const bool pred = (key[r] >= lo) && (key[r] <= hi);
;       const u64 bal = __builtin_amdgcn_ballot_w64(pred);
;       const int pos = base + __builtin_amdgcn_mbcnt_hi((unsigned)(bal >> 32), __builtin_amdgcn_mbcnt_lo((unsigned)bal, 0u));
;       if (pred) cand[pos] = key[r];
;       base += __builtin_popcountll(bal);
;     }
.LBB0_416:
	s_or_b64 exec, exec, s[0:1]
	s_bcnt1_i32_b64 s0, vcc
	s_add_i32 s6, s6, s0
	v_cmp_le_u32_e32 vcc, s79, v39
	v_cmp_ge_u32_e64 s[0:1], s78, v39
	s_and_b64 vcc, vcc, s[0:1]
	s_and_saveexec_b64 s[0:1], vcc
	v_mbcnt_lo_u32_b32 v26, vcc_lo, 0
	s_lshl_b32 s7, s6, 2
	v_mbcnt_hi_u32_b32 v26, vcc_hi, v26
	s_add_i32 s7, s7, s15
	v_lshl_add_u32 v26, v26, 2, s7
	ds_write_b32 v26, v39
.LBB0_418:
	s_or_b64 exec, exec, s[0:1]
	s_bcnt1_i32_b64 s0, vcc
	s_add_i32 s6, s6, s0
	v_cmp_le_u32_e32 vcc, s79, v37
	v_cmp_ge_u32_e64 s[0:1], s78, v37
	s_and_b64 vcc, vcc, s[0:1]
	s_and_saveexec_b64 s[0:1], vcc
	v_mbcnt_lo_u32_b32 v26, vcc_lo, 0
	s_lshl_b32 s7, s6, 2
	v_mbcnt_hi_u32_b32 v26, vcc_hi, v26
	s_add_i32 s7, s7, s15
	v_lshl_add_u32 v26, v26, 2, s7
	ds_write_b32 v26, v37
.LBB0_420:
	s_or_b64 exec, exec, s[0:1]
	s_bcnt1_i32_b64 s0, vcc
	s_add_i32 s6, s6, s0
	v_cmp_le_u32_e32 vcc, s79, v34
	v_cmp_ge_u32_e64 s[0:1], s78, v34
	s_and_b64 vcc, vcc, s[0:1]
	s_and_saveexec_b64 s[0:1], vcc
	v_mbcnt_lo_u32_b32 v26, vcc_lo, 0
	s_lshl_b32 s7, s6, 2
	v_mbcnt_hi_u32_b32 v26, vcc_hi, v26
	s_add_i32 s7, s7, s15
	v_lshl_add_u32 v26, v26, 2, s7
	ds_write_b32 v26, v34
.LBB0_422:
	s_or_b64 exec, exec, s[0:1]
	s_bcnt1_i32_b64 s0, vcc
	s_add_i32 s6, s6, s0
	v_cmp_le_u32_e32 vcc, s79, v32
	v_cmp_ge_u32_e64 s[0:1], s78, v32
	s_and_b64 vcc, vcc, s[0:1]
	s_and_saveexec_b64 s[0:1], vcc
	v_mbcnt_lo_u32_b32 v26, vcc_lo, 0
	s_lshl_b32 s7, s6, 2
	v_mbcnt_hi_u32_b32 v26, vcc_hi, v26
	s_add_i32 s7, s7, s15
	v_lshl_add_u32 v26, v26, 2, s7
	ds_write_b32 v26, v32
.LBB0_424:
	s_or_b64 exec, exec, s[0:1]
	s_bcnt1_i32_b64 s0, vcc
	s_add_i32 s6, s6, s0
	v_cmp_le_u32_e32 vcc, s79, v30
	v_cmp_ge_u32_e64 s[0:1], s78, v30
	s_and_b64 vcc, vcc, s[0:1]
	s_and_saveexec_b64 s[0:1], vcc
	v_mbcnt_lo_u32_b32 v26, vcc_lo, 0
	s_lshl_b32 s7, s6, 2
	v_mbcnt_hi_u32_b32 v26, vcc_hi, v26
	s_add_i32 s7, s7, s15
	v_lshl_add_u32 v26, v26, 2, s7
	ds_write_b32 v26, v30
.LBB0_426:
	s_or_b64 exec, exec, s[0:1]
	s_bcnt1_i32_b64 s0, vcc
	s_add_i32 s6, s6, s0
	v_cmp_le_u32_e32 vcc, s79, v28
	v_cmp_ge_u32_e64 s[0:1], s78, v28
	s_and_b64 vcc, vcc, s[0:1]
	s_and_saveexec_b64 s[0:1], vcc
	v_mbcnt_lo_u32_b32 v26, vcc_lo, 0
	s_lshl_b32 s7, s6, 2
	v_mbcnt_hi_u32_b32 v26, vcc_hi, v26
	s_add_i32 s7, s7, s15
	v_lshl_add_u32 v26, v26, 2, s7
	ds_write_b32 v26, v28
.LBB0_428:
	s_or_b64 exec, exec, s[0:1]
	s_bcnt1_i32_b64 s0, vcc
	s_add_i32 s6, s6, s0
	v_cmp_le_u32_e32 vcc, s79, v25
	v_cmp_ge_u32_e64 s[0:1], s78, v25
	s_and_b64 vcc, vcc, s[0:1]
	s_and_saveexec_b64 s[0:1], vcc
	v_mbcnt_lo_u32_b32 v26, vcc_lo, 0
	s_lshl_b32 s7, s6, 2
	v_mbcnt_hi_u32_b32 v26, vcc_hi, v26
	s_add_i32 s7, s7, s15
	v_lshl_add_u32 v26, v26, 2, s7
	ds_write_b32 v26, v25
.LBB0_430:
	s_or_b64 exec, exec, s[0:1]
	s_bcnt1_i32_b64 s0, vcc
	s_add_i32 s6, s6, s0
	v_cmp_le_u32_e32 vcc, s79, v23
	v_cmp_ge_u32_e64 s[0:1], s78, v23
	s_and_b64 vcc, vcc, s[0:1]
	s_and_saveexec_b64 s[0:1], vcc
	v_mbcnt_lo_u32_b32 v26, vcc_lo, 0
	s_lshl_b32 s7, s6, 2
	v_mbcnt_hi_u32_b32 v26, vcc_hi, v26
	s_add_i32 s7, s7, s15
	v_lshl_add_u32 v26, v26, 2, s7
	ds_write_b32 v26, v23
.LBB0_432:
	s_or_b64 exec, exec, s[0:1]
	s_bcnt1_i32_b64 s0, vcc
	s_add_i32 s6, s6, s0
	v_cmp_le_u32_e32 vcc, s79, v31
	v_cmp_ge_u32_e64 s[0:1], s78, v31
	s_and_b64 vcc, vcc, s[0:1]
	s_and_saveexec_b64 s[0:1], vcc
	v_mbcnt_lo_u32_b32 v26, vcc_lo, 0
	s_lshl_b32 s7, s6, 2
	v_mbcnt_hi_u32_b32 v26, vcc_hi, v26
	s_add_i32 s7, s7, s15
	v_lshl_add_u32 v26, v26, 2, s7
	ds_write_b32 v26, v31
.LBB0_434:
	s_or_b64 exec, exec, s[0:1]
	s_bcnt1_i32_b64 s0, vcc
	s_add_i32 s6, s6, s0
	v_cmp_le_u32_e32 vcc, s79, v29
	v_cmp_ge_u32_e64 s[0:1], s78, v29
	s_and_b64 vcc, vcc, s[0:1]
	s_and_saveexec_b64 s[0:1], vcc
	v_mbcnt_lo_u32_b32 v26, vcc_lo, 0
	s_lshl_b32 s7, s6, 2
	v_mbcnt_hi_u32_b32 v26, vcc_hi, v26
	s_add_i32 s7, s7, s15
	v_lshl_add_u32 v26, v26, 2, s7
	ds_write_b32 v26, v29
.LBB0_436:
	s_or_b64 exec, exec, s[0:1]
	s_bcnt1_i32_b64 s0, vcc
	s_add_i32 s6, s6, s0
	v_cmp_le_u32_e32 vcc, s79, v24
	v_cmp_ge_u32_e64 s[0:1], s78, v24
	s_and_b64 vcc, vcc, s[0:1]
	s_and_saveexec_b64 s[0:1], vcc
	v_mbcnt_lo_u32_b32 v26, vcc_lo, 0
	s_lshl_b32 s7, s6, 2
	v_mbcnt_hi_u32_b32 v26, vcc_hi, v26
	s_add_i32 s7, s7, s15
	v_lshl_add_u32 v26, v26, 2, s7
	ds_write_b32 v26, v24
.LBB0_438:
	s_or_b64 exec, exec, s[0:1]
	s_bcnt1_i32_b64 s0, vcc
	s_add_i32 s6, s6, s0
	v_cmp_le_u32_e32 vcc, s79, v22
	v_cmp_ge_u32_e64 s[0:1], s78, v22
	s_and_b64 vcc, vcc, s[0:1]
	s_and_saveexec_b64 s[0:1], vcc
	v_mbcnt_lo_u32_b32 v26, vcc_lo, 0
	s_lshl_b32 s7, s6, 2
	v_mbcnt_hi_u32_b32 v26, vcc_hi, v26
	s_add_i32 s7, s7, s15
	v_lshl_add_u32 v26, v26, 2, s7
	ds_write_b32 v26, v22
.LBB0_440:
	s_or_b64 exec, exec, s[0:1]
	s_bcnt1_i32_b64 s0, vcc
	s_add_i32 s6, s6, s0
	v_cmp_le_u32_e32 vcc, s79, v21
	v_cmp_ge_u32_e64 s[0:1], s78, v21
	s_and_b64 vcc, vcc, s[0:1]
	s_and_saveexec_b64 s[0:1], vcc
	v_mbcnt_lo_u32_b32 v26, vcc_lo, 0
	s_lshl_b32 s7, s6, 2
	v_mbcnt_hi_u32_b32 v26, vcc_hi, v26
	s_add_i32 s7, s7, s15
	v_lshl_add_u32 v26, v26, 2, s7
	ds_write_b32 v26, v21
.LBB0_442:
	s_or_b64 exec, exec, s[0:1]
	s_bcnt1_i32_b64 s0, vcc
	s_add_i32 s6, s6, s0
	v_cmp_le_u32_e32 vcc, s79, v19
	v_cmp_ge_u32_e64 s[0:1], s78, v19
	s_and_b64 vcc, vcc, s[0:1]
	s_and_saveexec_b64 s[0:1], vcc
	v_mbcnt_lo_u32_b32 v26, vcc_lo, 0
	s_lshl_b32 s7, s6, 2
	v_mbcnt_hi_u32_b32 v26, vcc_hi, v26
	s_add_i32 s7, s7, s15
	v_lshl_add_u32 v26, v26, 2, s7
	ds_write_b32 v26, v19
.LBB0_444:
	s_or_b64 exec, exec, s[0:1]
	s_bcnt1_i32_b64 s0, vcc
	s_add_i32 s6, s6, s0
	v_cmp_le_u32_e32 vcc, s79, v20
	v_cmp_ge_u32_e64 s[0:1], s78, v20
	s_and_b64 vcc, vcc, s[0:1]
	s_and_saveexec_b64 s[0:1], vcc
	v_mbcnt_lo_u32_b32 v26, vcc_lo, 0
	s_lshl_b32 s7, s6, 2
	v_mbcnt_hi_u32_b32 v26, vcc_hi, v26
	s_add_i32 s7, s7, s15
	v_lshl_add_u32 v26, v26, 2, s7
	ds_write_b32 v26, v20
; template <int NR>
; DI u64 select_wave(float* scw, int nreg, int lane) {
;     ...
;   if (!exact && lo < hi) {
;     unsigned* cand = reinterpret_cast<unsigned*>(scw);
;     int base = 0;
; #pragma unroll
;     for (int r = 0; r < NR; ++r) {
;       const bool pred = (key[r] >= lo) && (key[r] <= hi);
;       const u64 bal = __builtin_amdgcn_ballot_w64(pred);
;       const int pos = base + __builtin_amdgcn_mbcnt_hi((unsigned)(bal >> 32), __builtin_amdgcn_mbcnt_lo((unsigned)bal, 0u));
;       if (pred) cand[pos] = key[r];
;       base += __builtin_popcountll(bal);
;     }
.LBB0_446:
	s_or_b64 exec, exec, s[0:1]
	s_bcnt1_i32_b64 s0, vcc
	s_add_i32 s6, s6, s0
	v_cmp_le_u32_e32 vcc, s79, v18
	v_cmp_ge_u32_e64 s[0:1], s78, v18
	s_and_b64 vcc, vcc, s[0:1]
	s_and_saveexec_b64 s[0:1], vcc
	v_mbcnt_lo_u32_b32 v26, vcc_lo, 0
	s_lshl_b32 s7, s6, 2
	v_mbcnt_hi_u32_b32 v26, vcc_hi, v26
	s_add_i32 s7, s7, s15
	v_lshl_add_u32 v26, v26, 2, s7
	ds_write_b32 v26, v18
.LBB0_448:
	s_or_b64 exec, exec, s[0:1]
	s_bcnt1_i32_b64 s0, vcc
	s_add_i32 s6, s6, s0
	v_cmp_le_u32_e32 vcc, s79, v17
	v_cmp_ge_u32_e64 s[0:1], s78, v17
	s_and_b64 vcc, vcc, s[0:1]
	s_and_saveexec_b64 s[0:1], vcc
	v_mbcnt_lo_u32_b32 v26, vcc_lo, 0
	s_lshl_b32 s7, s6, 2
	v_mbcnt_hi_u32_b32 v26, vcc_hi, v26
	s_add_i32 s7, s7, s15
	v_lshl_add_u32 v26, v26, 2, s7
	ds_write_b32 v26, v17
.LBB0_450:
	s_or_b64 exec, exec, s[0:1]
	s_bcnt1_i32_b64 s0, vcc
	s_add_i32 s6, s6, s0
	v_cmp_le_u32_e32 vcc, s79, v16
	v_cmp_ge_u32_e64 s[0:1], s78, v16
	s_and_b64 vcc, vcc, s[0:1]
	s_and_saveexec_b64 s[0:1], vcc
	v_mbcnt_lo_u32_b32 v26, vcc_lo, 0
	s_lshl_b32 s7, s6, 2
	v_mbcnt_hi_u32_b32 v26, vcc_hi, v26
	s_add_i32 s7, s7, s15
	v_lshl_add_u32 v26, v26, 2, s7
	ds_write_b32 v26, v16
.LBB0_452:
	s_or_b64 exec, exec, s[0:1]
	s_bcnt1_i32_b64 s0, vcc
	s_add_i32 s6, s6, s0
	v_cmp_le_u32_e32 vcc, s79, v2
	v_cmp_ge_u32_e64 s[0:1], s78, v2
	s_and_b64 vcc, vcc, s[0:1]
	s_and_saveexec_b64 s[0:1], vcc
	v_mbcnt_lo_u32_b32 v26, vcc_lo, 0
	s_lshl_b32 s7, s6, 2
	v_mbcnt_hi_u32_b32 v26, vcc_hi, v26
	s_add_i32 s7, s7, s15
	v_lshl_add_u32 v26, v26, 2, s7
	ds_write_b32 v26, v2
.LBB0_454:
	s_or_b64 exec, exec, s[0:1]
	s_bcnt1_i32_b64 s0, vcc
	s_add_i32 s6, s6, s0
	v_cmp_le_u32_e32 vcc, s79, v4
	v_cmp_ge_u32_e64 s[0:1], s78, v4
	s_and_b64 vcc, vcc, s[0:1]
	s_and_saveexec_b64 s[0:1], vcc
	v_mbcnt_lo_u32_b32 v26, vcc_lo, 0
	s_lshl_b32 s7, s6, 2
	v_mbcnt_hi_u32_b32 v26, vcc_hi, v26
	s_add_i32 s7, s7, s15
	v_lshl_add_u32 v26, v26, 2, s7
	ds_write_b32 v26, v4
.LBB0_456:
	s_or_b64 exec, exec, s[0:1]
	s_bcnt1_i32_b64 s0, vcc
	s_add_i32 s6, s6, s0
	v_cmp_le_u32_e32 vcc, s79, v3
	v_cmp_ge_u32_e64 s[0:1], s78, v3
	s_and_b64 vcc, vcc, s[0:1]
	s_and_saveexec_b64 s[0:1], vcc
	v_mbcnt_lo_u32_b32 v26, vcc_lo, 0
	s_lshl_b32 s7, s6, 2
	v_mbcnt_hi_u32_b32 v26, vcc_hi, v26
	s_add_i32 s7, s7, s15
	v_lshl_add_u32 v26, v26, 2, s7
	ds_write_b32 v26, v3
.LBB0_458:
	s_or_b64 exec, exec, s[0:1]
	s_bcnt1_i32_b64 s0, vcc
	s_add_i32 s6, s6, s0
	v_cmp_le_u32_e32 vcc, s79, v6
	v_cmp_ge_u32_e64 s[0:1], s78, v6
	s_and_b64 vcc, vcc, s[0:1]
	s_and_saveexec_b64 s[0:1], vcc
	v_mbcnt_lo_u32_b32 v26, vcc_lo, 0
	s_lshl_b32 s7, s6, 2
	v_mbcnt_hi_u32_b32 v26, vcc_hi, v26
	s_add_i32 s7, s7, s15
	v_lshl_add_u32 v26, v26, 2, s7
	ds_write_b32 v26, v6
.LBB0_460:
	s_or_b64 exec, exec, s[0:1]
	s_bcnt1_i32_b64 s0, vcc
	s_add_i32 s6, s6, s0
	v_cmp_le_u32_e32 vcc, s79, v5
	v_cmp_ge_u32_e64 s[0:1], s78, v5
	s_and_b64 vcc, vcc, s[0:1]
	s_and_saveexec_b64 s[0:1], vcc
	v_mbcnt_lo_u32_b32 v26, vcc_lo, 0
	s_lshl_b32 s7, s6, 2
	v_mbcnt_hi_u32_b32 v26, vcc_hi, v26
	s_add_i32 s7, s7, s15
	v_lshl_add_u32 v26, v26, 2, s7
	ds_write_b32 v26, v5
.LBB0_462:
	s_or_b64 exec, exec, s[0:1]
	s_bcnt1_i32_b64 s0, vcc
	s_add_i32 s6, s6, s0
	v_cmp_le_u32_e32 vcc, s79, v8
	v_cmp_ge_u32_e64 s[0:1], s78, v8
	s_and_b64 vcc, vcc, s[0:1]
	s_and_saveexec_b64 s[0:1], vcc
	v_mbcnt_lo_u32_b32 v26, vcc_lo, 0
	s_lshl_b32 s7, s6, 2
	v_mbcnt_hi_u32_b32 v26, vcc_hi, v26
	s_add_i32 s7, s7, s15
	v_lshl_add_u32 v26, v26, 2, s7
	ds_write_b32 v26, v8
.LBB0_464:
	s_or_b64 exec, exec, s[0:1]
	s_bcnt1_i32_b64 s0, vcc
	s_add_i32 s6, s6, s0
	v_cmp_le_u32_e32 vcc, s79, v7
	v_cmp_ge_u32_e64 s[0:1], s78, v7
	s_and_b64 vcc, vcc, s[0:1]
	s_and_saveexec_b64 s[0:1], vcc
	v_mbcnt_lo_u32_b32 v26, vcc_lo, 0
	s_lshl_b32 s7, s6, 2
	v_mbcnt_hi_u32_b32 v26, vcc_hi, v26
	s_add_i32 s7, s7, s15
	v_lshl_add_u32 v26, v26, 2, s7
	ds_write_b32 v26, v7
.LBB0_466:
	s_or_b64 exec, exec, s[0:1]
	s_bcnt1_i32_b64 s0, vcc
	s_add_i32 s6, s6, s0
	v_cmp_le_u32_e32 vcc, s79, v11
	v_cmp_ge_u32_e64 s[0:1], s78, v11
	s_and_b64 vcc, vcc, s[0:1]
	s_and_saveexec_b64 s[0:1], vcc
	v_mbcnt_lo_u32_b32 v26, vcc_lo, 0
	s_lshl_b32 s7, s6, 2
	v_mbcnt_hi_u32_b32 v26, vcc_hi, v26
	s_add_i32 s7, s7, s15
	v_lshl_add_u32 v26, v26, 2, s7
	ds_write_b32 v26, v11
.LBB0_468:
	s_or_b64 exec, exec, s[0:1]
	s_bcnt1_i32_b64 s0, vcc
	s_add_i32 s6, s6, s0
	v_cmp_le_u32_e32 vcc, s79, v9
	v_cmp_ge_u32_e64 s[0:1], s78, v9
	s_and_b64 vcc, vcc, s[0:1]
	s_and_saveexec_b64 s[0:1], vcc
	v_mbcnt_lo_u32_b32 v26, vcc_lo, 0
	s_lshl_b32 s7, s6, 2
	v_mbcnt_hi_u32_b32 v26, vcc_hi, v26
	s_add_i32 s7, s7, s15
	v_lshl_add_u32 v26, v26, 2, s7
	ds_write_b32 v26, v9
.LBB0_470:
	s_or_b64 exec, exec, s[0:1]
	s_bcnt1_i32_b64 s0, vcc
	s_add_i32 s6, s6, s0
	v_cmp_le_u32_e32 vcc, s79, v12
	v_cmp_ge_u32_e64 s[0:1], s78, v12
	s_and_b64 vcc, vcc, s[0:1]
	s_and_saveexec_b64 s[0:1], vcc
	v_mbcnt_lo_u32_b32 v26, vcc_lo, 0
	s_lshl_b32 s7, s6, 2
	v_mbcnt_hi_u32_b32 v26, vcc_hi, v26
	s_add_i32 s7, s7, s15
	v_lshl_add_u32 v26, v26, 2, s7
	ds_write_b32 v26, v12
.LBB0_472:
	s_or_b64 exec, exec, s[0:1]
	s_bcnt1_i32_b64 s0, vcc
	s_add_i32 s6, s6, s0
	v_cmp_le_u32_e32 vcc, s79, v10
	v_cmp_ge_u32_e64 s[0:1], s78, v10
	s_and_b64 vcc, vcc, s[0:1]
	s_and_saveexec_b64 s[0:1], vcc
	v_mbcnt_lo_u32_b32 v26, vcc_lo, 0
	s_lshl_b32 s7, s6, 2
	v_mbcnt_hi_u32_b32 v26, vcc_hi, v26
	s_add_i32 s7, s7, s15
	v_lshl_add_u32 v26, v26, 2, s7
	ds_write_b32 v26, v10
.LBB0_474:
	s_or_b64 exec, exec, s[0:1]
	s_bcnt1_i32_b64 s0, vcc
	s_add_i32 s6, s6, s0
	v_cmp_le_u32_e32 vcc, s79, v14
	v_cmp_ge_u32_e64 s[0:1], s78, v14
	s_and_b64 vcc, vcc, s[0:1]
	s_and_saveexec_b64 s[0:1], vcc
	v_mbcnt_lo_u32_b32 v26, vcc_lo, 0
	s_lshl_b32 s7, s6, 2
	v_mbcnt_hi_u32_b32 v26, vcc_hi, v26
	s_add_i32 s7, s7, s15
	v_lshl_add_u32 v26, v26, 2, s7
	ds_write_b32 v26, v14
.LBB0_476:
	s_or_b64 exec, exec, s[0:1]
	s_bcnt1_i32_b64 s0, vcc
	s_add_i32 s6, s6, s0
	v_cmp_le_u32_e32 vcc, s79, v13
	v_cmp_ge_u32_e64 s[0:1], s78, v13
	s_and_b64 vcc, vcc, s[0:1]
	s_and_saveexec_b64 s[0:1], vcc
	v_mbcnt_lo_u32_b32 v26, vcc_lo, 0
	s_lshl_b32 s7, s6, 2
	v_mbcnt_hi_u32_b32 v26, vcc_hi, v26
	s_add_i32 s7, s7, s15
	v_lshl_add_u32 v26, v26, 2, s7
	ds_write_b32 v26, v13
.LBB0_478:
	s_or_b64 exec, exec, s[0:1]
	s_bcnt1_i32_b64 s0, vcc
	s_add_i32 s6, s6, s0
	v_cmp_le_u32_e32 vcc, s79, v51
	v_cmp_ge_u32_e64 s[0:1], s78, v51
	s_and_b64 vcc, vcc, s[0:1]
	s_and_saveexec_b64 s[0:1], vcc
	v_mbcnt_lo_u32_b32 v26, vcc_lo, 0
	s_lshl_b32 s7, s6, 2
	v_mbcnt_hi_u32_b32 v26, vcc_hi, v26
	s_add_i32 s7, s7, s15
	v_lshl_add_u32 v26, v26, 2, s7
	ds_write_b32 v26, v51

; template <int NR>
; DI u64 select_wave(float* scw, int nreg, int lane) {
;     ...
;   if (!exact && lo < hi) {
;     unsigned* cand = reinterpret_cast<unsigned*>(scw);
;     int base = 0;
; #pragma unroll
;     for (int r = 0; r < NR; ++r) {
;       const bool pred = (key[r] >= lo) && (key[r] <= hi);
;       const u64 bal = __builtin_amdgcn_ballot_w64(pred);
;       const int pos = base + __builtin_amdgcn_mbcnt_hi((unsigned)(bal >> 32), __builtin_amdgcn_mbcnt_lo((unsigned)bal, 0u));
;       if (pred) cand[pos] = key[r];
;       base += __builtin_popcountll(bal);
;     }
.LBB0_512:
	s_mov_b64 s[2:3], -1
	s_and_b64 vcc, exec, s[0:1]
	s_cbranch_vccnz .LBB0_587
	s_cmp_ge_u32 s23, s22
	s_mov_b64 s[0:1], 0
	s_cbranch_scc1 .LBB0_585
	v_cmp_le_u32_e32 vcc, s23, v28
	v_cmp_ge_u32_e64 s[0:1], s22, v28
	s_and_b64 vcc, vcc, s[0:1]
	s_and_saveexec_b64 s[0:1], vcc
	v_mbcnt_lo_u32_b32 v26, vcc_lo, 0
	v_mbcnt_hi_u32_b32 v26, vcc_hi, v26
	v_lshl_add_u32 v26, v26, 2, s15
	ds_write_b32 v26, v28
	s_or_b64 exec, exec, s[0:1]
	s_bcnt1_i32_b64 s6, vcc
	v_cmp_le_u32_e32 vcc, s23, v3
	v_cmp_ge_u32_e64 s[0:1], s22, v3
	s_and_b64 vcc, vcc, s[0:1]
	s_and_saveexec_b64 s[0:1], vcc
	v_mbcnt_lo_u32_b32 v26, vcc_lo, 0
	s_lshl_b32 s7, s6, 2
	v_mbcnt_hi_u32_b32 v26, vcc_hi, v26
	s_add_i32 s7, s7, s15
	v_lshl_add_u32 v26, v26, 2, s7
	ds_write_b32 v26, v3
.LBB0_518:
	s_or_b64 exec, exec, s[0:1]
	s_bcnt1_i32_b64 s0, vcc
	s_add_i32 s6, s0, s6
	v_cmp_le_u32_e32 vcc, s23, v2
	v_cmp_ge_u32_e64 s[0:1], s22, v2
	s_and_b64 vcc, vcc, s[0:1]
	s_and_saveexec_b64 s[0:1], vcc
	v_mbcnt_lo_u32_b32 v26, vcc_lo, 0
	s_lshl_b32 s7, s6, 2
	v_mbcnt_hi_u32_b32 v26, vcc_hi, v26
	s_add_i32 s7, s7, s15
	v_lshl_add_u32 v26, v26, 2, s7
	ds_write_b32 v26, v2
.LBB0_520:
	s_or_b64 exec, exec, s[0:1]
	s_bcnt1_i32_b64 s0, vcc
	s_add_i32 s6, s6, s0
	v_cmp_le_u32_e32 vcc, s23, v5
	v_cmp_ge_u32_e64 s[0:1], s22, v5
	s_and_b64 vcc, vcc, s[0:1]
	s_and_saveexec_b64 s[0:1], vcc
	v_mbcnt_lo_u32_b32 v26, vcc_lo, 0
	s_lshl_b32 s7, s6, 2
	v_mbcnt_hi_u32_b32 v26, vcc_hi, v26
	s_add_i32 s7, s7, s15
	v_lshl_add_u32 v26, v26, 2, s7
	ds_write_b32 v26, v5
.LBB0_522:
	s_or_b64 exec, exec, s[0:1]
	s_bcnt1_i32_b64 s0, vcc
	s_add_i32 s6, s6, s0
	v_cmp_le_u32_e32 vcc, s23, v4
	v_cmp_ge_u32_e64 s[0:1], s22, v4
	s_and_b64 vcc, vcc, s[0:1]
	s_and_saveexec_b64 s[0:1], vcc
	v_mbcnt_lo_u32_b32 v26, vcc_lo, 0
	s_lshl_b32 s7, s6, 2
	v_mbcnt_hi_u32_b32 v26, vcc_hi, v26
	s_add_i32 s7, s7, s15
	v_lshl_add_u32 v26, v26, 2, s7
	ds_write_b32 v26, v4
.LBB0_524:
	s_or_b64 exec, exec, s[0:1]
	s_bcnt1_i32_b64 s0, vcc
	s_add_i32 s6, s6, s0
	v_cmp_le_u32_e32 vcc, s23, v7
	v_cmp_ge_u32_e64 s[0:1], s22, v7
	s_and_b64 vcc, vcc, s[0:1]
	s_and_saveexec_b64 s[0:1], vcc
	v_mbcnt_lo_u32_b32 v26, vcc_lo, 0
	s_lshl_b32 s7, s6, 2
	v_mbcnt_hi_u32_b32 v26, vcc_hi, v26
	s_add_i32 s7, s7, s15
	v_lshl_add_u32 v26, v26, 2, s7
	ds_write_b32 v26, v7
.LBB0_526:
	s_or_b64 exec, exec, s[0:1]
	s_bcnt1_i32_b64 s0, vcc
	s_add_i32 s6, s6, s0
	v_cmp_le_u32_e32 vcc, s23, v6
	v_cmp_ge_u32_e64 s[0:1], s22, v6
	s_and_b64 vcc, vcc, s[0:1]
	s_and_saveexec_b64 s[0:1], vcc
	v_mbcnt_lo_u32_b32 v26, vcc_lo, 0
	s_lshl_b32 s7, s6, 2
	v_mbcnt_hi_u32_b32 v26, vcc_hi, v26
	s_add_i32 s7, s7, s15
	v_lshl_add_u32 v26, v26, 2, s7
	ds_write_b32 v26, v6
.LBB0_528:
	s_or_b64 exec, exec, s[0:1]
	s_bcnt1_i32_b64 s0, vcc
	s_add_i32 s6, s6, s0
	v_cmp_le_u32_e32 vcc, s23, v9
	v_cmp_ge_u32_e64 s[0:1], s22, v9
	s_and_b64 vcc, vcc, s[0:1]
	s_and_saveexec_b64 s[0:1], vcc
	v_mbcnt_lo_u32_b32 v26, vcc_lo, 0
	s_lshl_b32 s7, s6, 2
	v_mbcnt_hi_u32_b32 v26, vcc_hi, v26
	s_add_i32 s7, s7, s15
	v_lshl_add_u32 v26, v26, 2, s7
	ds_write_b32 v26, v9
.LBB0_530:
	s_or_b64 exec, exec, s[0:1]
	s_bcnt1_i32_b64 s0, vcc
	s_add_i32 s6, s6, s0
	v_cmp_le_u32_e32 vcc, s23, v8
	v_cmp_ge_u32_e64 s[0:1], s22, v8
	s_and_b64 vcc, vcc, s[0:1]
	s_and_saveexec_b64 s[0:1], vcc
	v_mbcnt_lo_u32_b32 v26, vcc_lo, 0
	s_lshl_b32 s7, s6, 2
	v_mbcnt_hi_u32_b32 v26, vcc_hi, v26
	s_add_i32 s7, s7, s15
	v_lshl_add_u32 v26, v26, 2, s7
	ds_write_b32 v26, v8
.LBB0_532:
	s_or_b64 exec, exec, s[0:1]
	s_bcnt1_i32_b64 s0, vcc
	s_add_i32 s6, s6, s0
	v_cmp_le_u32_e32 vcc, s23, v11
	v_cmp_ge_u32_e64 s[0:1], s22, v11
	s_and_b64 vcc, vcc, s[0:1]
	s_and_saveexec_b64 s[0:1], vcc
	v_mbcnt_lo_u32_b32 v26, vcc_lo, 0
	s_lshl_b32 s7, s6, 2
	v_mbcnt_hi_u32_b32 v26, vcc_hi, v26
	s_add_i32 s7, s7, s15
	v_lshl_add_u32 v26, v26, 2, s7
	ds_write_b32 v26, v11
.LBB0_534:
	s_or_b64 exec, exec, s[0:1]
	s_bcnt1_i32_b64 s0, vcc
	s_add_i32 s6, s6, s0
	v_cmp_le_u32_e32 vcc, s23, v10
	v_cmp_ge_u32_e64 s[0:1], s22, v10
	s_and_b64 vcc, vcc, s[0:1]
	s_and_saveexec_b64 s[0:1], vcc
	v_mbcnt_lo_u32_b32 v26, vcc_lo, 0
	s_lshl_b32 s7, s6, 2
	v_mbcnt_hi_u32_b32 v26, vcc_hi, v26
	s_add_i32 s7, s7, s15
	v_lshl_add_u32 v26, v26, 2, s7
	ds_write_b32 v26, v10
.LBB0_536:
	s_or_b64 exec, exec, s[0:1]
	s_bcnt1_i32_b64 s0, vcc
	s_add_i32 s6, s6, s0
	v_cmp_le_u32_e32 vcc, s23, v13
	v_cmp_ge_u32_e64 s[0:1], s22, v13
	s_and_b64 vcc, vcc, s[0:1]
	s_and_saveexec_b64 s[0:1], vcc
	v_mbcnt_lo_u32_b32 v26, vcc_lo, 0
	s_lshl_b32 s7, s6, 2
	v_mbcnt_hi_u32_b32 v26, vcc_hi, v26
	s_add_i32 s7, s7, s15
	v_lshl_add_u32 v26, v26, 2, s7
	ds_write_b32 v26, v13
.LBB0_538:
	s_or_b64 exec, exec, s[0:1]
	s_bcnt1_i32_b64 s0, vcc
	s_add_i32 s6, s6, s0
	v_cmp_le_u32_e32 vcc, s23, v12
	v_cmp_ge_u32_e64 s[0:1], s22, v12
	s_and_b64 vcc, vcc, s[0:1]
	s_and_saveexec_b64 s[0:1], vcc
	v_mbcnt_lo_u32_b32 v26, vcc_lo, 0
	s_lshl_b32 s7, s6, 2
	v_mbcnt_hi_u32_b32 v26, vcc_hi, v26
	s_add_i32 s7, s7, s15
	v_lshl_add_u32 v26, v26, 2, s7
	ds_write_b32 v26, v12
.LBB0_540:
	s_or_b64 exec, exec, s[0:1]
	s_bcnt1_i32_b64 s0, vcc
	s_add_i32 s6, s6, s0
	v_cmp_le_u32_e32 vcc, s23, v15
	v_cmp_ge_u32_e64 s[0:1], s22, v15
	s_and_b64 vcc, vcc, s[0:1]
	s_and_saveexec_b64 s[0:1], vcc
	v_mbcnt_lo_u32_b32 v26, vcc_lo, 0
	s_lshl_b32 s7, s6, 2
	v_mbcnt_hi_u32_b32 v26, vcc_hi, v26
	s_add_i32 s7, s7, s15
	v_lshl_add_u32 v26, v26, 2, s7
	ds_write_b32 v26, v15
.LBB0_542:
	s_or_b64 exec, exec, s[0:1]
	s_bcnt1_i32_b64 s0, vcc
	s_add_i32 s6, s6, s0
	v_cmp_le_u32_e32 vcc, s23, v14
	v_cmp_ge_u32_e64 s[0:1], s22, v14
	s_and_b64 vcc, vcc, s[0:1]
	s_and_saveexec_b64 s[0:1], vcc
	v_mbcnt_lo_u32_b32 v26, vcc_lo, 0
	s_lshl_b32 s7, s6, 2
	v_mbcnt_hi_u32_b32 v26, vcc_hi, v26
	s_add_i32 s7, s7, s15
	v_lshl_add_u32 v26, v26, 2, s7
	ds_write_b32 v26, v14
; template <int NR>
; DI u64 select_wave(float* scw, int nreg, int lane) {
;     ...
;   if (!exact && lo < hi) {
;     unsigned* cand = reinterpret_cast<unsigned*>(scw);
;     int base = 0;
; #pragma unroll
;     for (int r = 0; r < NR; ++r) {
;       const bool pred = (key[r] >= lo) && (key[r] <= hi);
;       const u64 bal = __builtin_amdgcn_ballot_w64(pred);
;       const int pos = base + __builtin_amdgcn_mbcnt_hi((unsigned)(bal >> 32), __builtin_amdgcn_mbcnt_lo((unsigned)bal, 0u));
;       if (pred) cand[pos] = key[r];
;       base += __builtin_popcountll(bal);
;     }
.LBB0_544:
	s_or_b64 exec, exec, s[0:1]
	s_bcnt1_i32_b64 s0, vcc
	s_add_i32 s6, s6, s0
	v_cmp_le_u32_e32 vcc, s23, v17
	v_cmp_ge_u32_e64 s[0:1], s22, v17
	s_and_b64 vcc, vcc, s[0:1]
	s_and_saveexec_b64 s[0:1], vcc
	v_mbcnt_lo_u32_b32 v26, vcc_lo, 0
	s_lshl_b32 s7, s6, 2
	v_mbcnt_hi_u32_b32 v26, vcc_hi, v26
	s_add_i32 s7, s7, s15
	v_lshl_add_u32 v26, v26, 2, s7
	ds_write_b32 v26, v17
.LBB0_546:
	s_or_b64 exec, exec, s[0:1]
	s_bcnt1_i32_b64 s0, vcc
	s_add_i32 s6, s6, s0
	v_cmp_le_u32_e32 vcc, s23, v16
	v_cmp_ge_u32_e64 s[0:1], s22, v16
	s_and_b64 vcc, vcc, s[0:1]
	s_and_saveexec_b64 s[0:1], vcc
	v_mbcnt_lo_u32_b32 v26, vcc_lo, 0
	s_lshl_b32 s7, s6, 2
	v_mbcnt_hi_u32_b32 v26, vcc_hi, v26
	s_add_i32 s7, s7, s15
	v_lshl_add_u32 v26, v26, 2, s7
	ds_write_b32 v26, v16
.LBB0_548:
	s_or_b64 exec, exec, s[0:1]
	s_bcnt1_i32_b64 s0, vcc
	s_add_i32 s6, s6, s0
	v_cmp_le_u32_e32 vcc, s23, v19
	v_cmp_ge_u32_e64 s[0:1], s22, v19
	s_and_b64 vcc, vcc, s[0:1]
	s_and_saveexec_b64 s[0:1], vcc
	v_mbcnt_lo_u32_b32 v26, vcc_lo, 0
	s_lshl_b32 s7, s6, 2
	v_mbcnt_hi_u32_b32 v26, vcc_hi, v26
	s_add_i32 s7, s7, s15
	v_lshl_add_u32 v26, v26, 2, s7
	ds_write_b32 v26, v19
.LBB0_550:
	s_or_b64 exec, exec, s[0:1]
	s_bcnt1_i32_b64 s0, vcc
	s_add_i32 s6, s6, s0
	v_cmp_le_u32_e32 vcc, s23, v18
	v_cmp_ge_u32_e64 s[0:1], s22, v18
	s_and_b64 vcc, vcc, s[0:1]
	s_and_saveexec_b64 s[0:1], vcc
	v_mbcnt_lo_u32_b32 v26, vcc_lo, 0
	s_lshl_b32 s7, s6, 2
	v_mbcnt_hi_u32_b32 v26, vcc_hi, v26
	s_add_i32 s7, s7, s15
	v_lshl_add_u32 v26, v26, 2, s7
	ds_write_b32 v26, v18
.LBB0_552:
	s_or_b64 exec, exec, s[0:1]
	s_bcnt1_i32_b64 s0, vcc
	s_add_i32 s6, s6, s0
	v_cmp_le_u32_e32 vcc, s23, v21
	v_cmp_ge_u32_e64 s[0:1], s22, v21
	s_and_b64 vcc, vcc, s[0:1]
	s_and_saveexec_b64 s[0:1], vcc
	v_mbcnt_lo_u32_b32 v26, vcc_lo, 0
	s_lshl_b32 s7, s6, 2
	v_mbcnt_hi_u32_b32 v26, vcc_hi, v26
	s_add_i32 s7, s7, s15
	v_lshl_add_u32 v26, v26, 2, s7
	ds_write_b32 v26, v21
.LBB0_554:
	s_or_b64 exec, exec, s[0:1]
	s_bcnt1_i32_b64 s0, vcc
	s_add_i32 s6, s6, s0
	v_cmp_le_u32_e32 vcc, s23, v20
	v_cmp_ge_u32_e64 s[0:1], s22, v20
	s_and_b64 vcc, vcc, s[0:1]
	s_and_saveexec_b64 s[0:1], vcc
	v_mbcnt_lo_u32_b32 v26, vcc_lo, 0
	s_lshl_b32 s7, s6, 2
	v_mbcnt_hi_u32_b32 v26, vcc_hi, v26
	s_add_i32 s7, s7, s15
	v_lshl_add_u32 v26, v26, 2, s7
	ds_write_b32 v26, v20
.LBB0_556:
	s_or_b64 exec, exec, s[0:1]
	s_bcnt1_i32_b64 s0, vcc
	s_add_i32 s6, s6, s0
	v_cmp_le_u32_e32 vcc, s23, v23
	v_cmp_ge_u32_e64 s[0:1], s22, v23
	s_and_b64 vcc, vcc, s[0:1]
	s_and_saveexec_b64 s[0:1], vcc
	v_mbcnt_lo_u32_b32 v26, vcc_lo, 0
	s_lshl_b32 s7, s6, 2
	v_mbcnt_hi_u32_b32 v26, vcc_hi, v26
	s_add_i32 s7, s7, s15
	v_lshl_add_u32 v26, v26, 2, s7
	ds_write_b32 v26, v23
.LBB0_558:
	s_or_b64 exec, exec, s[0:1]
	s_bcnt1_i32_b64 s0, vcc
	s_add_i32 s6, s6, s0
	v_cmp_le_u32_e32 vcc, s23, v22
	v_cmp_ge_u32_e64 s[0:1], s22, v22
	s_and_b64 vcc, vcc, s[0:1]
	s_and_saveexec_b64 s[0:1], vcc
	v_mbcnt_lo_u32_b32 v26, vcc_lo, 0
	s_lshl_b32 s7, s6, 2
	v_mbcnt_hi_u32_b32 v26, vcc_hi, v26
	s_add_i32 s7, s7, s15
	v_lshl_add_u32 v26, v26, 2, s7
	ds_write_b32 v26, v22
.LBB0_560:
	s_or_b64 exec, exec, s[0:1]
	s_bcnt1_i32_b64 s0, vcc
	s_add_i32 s6, s6, s0
	v_cmp_le_u32_e32 vcc, s23, v25
	v_cmp_ge_u32_e64 s[0:1], s22, v25
	s_and_b64 vcc, vcc, s[0:1]
	s_and_saveexec_b64 s[0:1], vcc
	v_mbcnt_lo_u32_b32 v26, vcc_lo, 0
	s_lshl_b32 s7, s6, 2
	v_mbcnt_hi_u32_b32 v26, vcc_hi, v26
	s_add_i32 s7, s7, s15
	v_lshl_add_u32 v26, v26, 2, s7
	ds_write_b32 v26, v25
.LBB0_562:
	s_or_b64 exec, exec, s[0:1]
	s_bcnt1_i32_b64 s0, vcc
	s_add_i32 s6, s6, s0
	v_cmp_le_u32_e32 vcc, s23, v24
	v_cmp_ge_u32_e64 s[0:1], s22, v24
	s_and_b64 vcc, vcc, s[0:1]
	s_and_saveexec_b64 s[0:1], vcc
	v_mbcnt_lo_u32_b32 v26, vcc_lo, 0
	s_lshl_b32 s7, s6, 2
	v_mbcnt_hi_u32_b32 v26, vcc_hi, v26
	s_add_i32 s7, s7, s15
	v_lshl_add_u32 v26, v26, 2, s7
	ds_write_b32 v26, v24
.LBB0_564:
	s_or_b64 exec, exec, s[0:1]
	s_bcnt1_i32_b64 s0, vcc
	s_add_i32 s6, s6, s0
	v_cmp_le_u32_e32 vcc, s23, v29
	v_cmp_ge_u32_e64 s[0:1], s22, v29
	s_and_b64 vcc, vcc, s[0:1]
	s_and_saveexec_b64 s[0:1], vcc
	v_mbcnt_lo_u32_b32 v26, vcc_lo, 0
	s_lshl_b32 s7, s6, 2
	v_mbcnt_hi_u32_b32 v26, vcc_hi, v26
	s_add_i32 s7, s7, s15
	v_lshl_add_u32 v26, v26, 2, s7
	ds_write_b32 v26, v29
.LBB0_566:
	s_or_b64 exec, exec, s[0:1]
	s_bcnt1_i32_b64 s0, vcc
	s_add_i32 s6, s6, s0
	v_cmp_le_u32_e32 vcc, s23, v30
	v_cmp_ge_u32_e64 s[0:1], s22, v30
	s_and_b64 vcc, vcc, s[0:1]
	s_and_saveexec_b64 s[0:1], vcc
	v_mbcnt_lo_u32_b32 v26, vcc_lo, 0
	s_lshl_b32 s7, s6, 2
	v_mbcnt_hi_u32_b32 v26, vcc_hi, v26
	s_add_i32 s7, s7, s15
	v_lshl_add_u32 v26, v26, 2, s7
	ds_write_b32 v26, v30
.LBB0_568:
	s_or_b64 exec, exec, s[0:1]
	s_bcnt1_i32_b64 s0, vcc
	s_add_i32 s6, s6, s0
	v_cmp_le_u32_e32 vcc, s23, v31
	v_cmp_ge_u32_e64 s[0:1], s22, v31
	s_and_b64 vcc, vcc, s[0:1]
	s_and_saveexec_b64 s[0:1], vcc
	v_mbcnt_lo_u32_b32 v26, vcc_lo, 0
	s_lshl_b32 s7, s6, 2
	v_mbcnt_hi_u32_b32 v26, vcc_hi, v26
	s_add_i32 s7, s7, s15
	v_lshl_add_u32 v26, v26, 2, s7
	ds_write_b32 v26, v31
.LBB0_570:
	s_or_b64 exec, exec, s[0:1]
	s_bcnt1_i32_b64 s0, vcc
	s_add_i32 s6, s6, s0
	v_cmp_le_u32_e32 vcc, s23, v32
	v_cmp_ge_u32_e64 s[0:1], s22, v32
	s_and_b64 vcc, vcc, s[0:1]
	s_and_saveexec_b64 s[0:1], vcc
	v_mbcnt_lo_u32_b32 v26, vcc_lo, 0
	s_lshl_b32 s7, s6, 2
	v_mbcnt_hi_u32_b32 v26, vcc_hi, v26
	s_add_i32 s7, s7, s15
	v_lshl_add_u32 v26, v26, 2, s7
	ds_write_b32 v26, v32
.LBB0_572:
	s_or_b64 exec, exec, s[0:1]
	s_bcnt1_i32_b64 s0, vcc
	s_add_i32 s6, s6, s0
	v_cmp_le_u32_e32 vcc, s23, v33
	v_cmp_ge_u32_e64 s[0:1], s22, v33
	s_and_b64 vcc, vcc, s[0:1]
	s_and_saveexec_b64 s[0:1], vcc
	v_mbcnt_lo_u32_b32 v26, vcc_lo, 0
	s_lshl_b32 s7, s6, 2
	v_mbcnt_hi_u32_b32 v26, vcc_hi, v26
	s_add_i32 s7, s7, s15
	v_lshl_add_u32 v26, v26, 2, s7
	ds_write_b32 v26, v33
.LBB0_574:
	s_or_b64 exec, exec, s[0:1]
	s_bcnt1_i32_b64 s0, vcc
	s_add_i32 s6, s6, s0
	v_cmp_le_u32_e32 vcc, s23, v34
	v_cmp_ge_u32_e64 s[0:1], s22, v34
	s_and_b64 vcc, vcc, s[0:1]
	s_and_saveexec_b64 s[0:1], vcc
	v_mbcnt_lo_u32_b32 v26, vcc_lo, 0
	s_lshl_b32 s7, s6, 2
	v_mbcnt_hi_u32_b32 v26, vcc_hi, v26
	s_add_i32 s7, s7, s15
	v_lshl_add_u32 v26, v26, 2, s7
	ds_write_b32 v26, v34

; template <int NR>
; DI u64 select_wave(float* scw, int nreg, int lane) {
;     ...
;   if (!exact && lo < hi) {
;     unsigned* cand = reinterpret_cast<unsigned*>(scw);
;     int base = 0;
; #pragma unroll
;     for (int r = 0; r < NR; ++r) {
;       const bool pred = (key[r] >= lo) && (key[r] <= hi);
;       const u64 bal = __builtin_amdgcn_ballot_w64(pred);
;       const int pos = base + __builtin_amdgcn_mbcnt_hi((unsigned)(bal >> 32), __builtin_amdgcn_mbcnt_lo((unsigned)bal, 0u));
;       if (pred) cand[pos] = key[r];
;       base += __builtin_popcountll(bal);
;     }
.LBB0_607:
	s_mov_b64 s[2:3], -1
	s_and_b64 vcc, exec, s[0:1]
	s_cbranch_vccnz .LBB0_666
	s_cmp_ge_u32 s23, s22
	s_mov_b64 s[0:1], 0
	s_cbranch_scc1 .LBB0_664
	v_cmp_le_u32_e32 vcc, s23, v18
	v_cmp_ge_u32_e64 s[0:1], s22, v18
	s_and_b64 vcc, vcc, s[0:1]
	s_and_saveexec_b64 s[0:1], vcc
	v_mbcnt_lo_u32_b32 v26, vcc_lo, 0
	v_mbcnt_hi_u32_b32 v26, vcc_hi, v26
	v_lshl_add_u32 v26, v26, 2, s15
	ds_write_b32 v26, v18
	s_or_b64 exec, exec, s[0:1]
	s_bcnt1_i32_b64 s6, vcc
	v_cmp_le_u32_e32 vcc, s23, v3
	v_cmp_ge_u32_e64 s[0:1], s22, v3
	s_and_b64 vcc, vcc, s[0:1]
	s_and_saveexec_b64 s[0:1], vcc
	v_mbcnt_lo_u32_b32 v26, vcc_lo, 0
	s_lshl_b32 s7, s6, 2
	v_mbcnt_hi_u32_b32 v26, vcc_hi, v26
	s_add_i32 s7, s7, s15
	v_lshl_add_u32 v26, v26, 2, s7
	ds_write_b32 v26, v3

; template <int NR>
; DI u64 select_wave(float* scw, int nreg, int lane) {
;     ...
;   if (!exact && lo < hi) {
;     unsigned* cand = reinterpret_cast<unsigned*>(scw);
;     int base = 0;
; #pragma unroll
;     for (int r = 0; r < NR; ++r) {
;       const bool pred = (key[r] >= lo) && (key[r] <= hi);
;       const u64 bal = __builtin_amdgcn_ballot_w64(pred);
;       const int pos = base + __builtin_amdgcn_mbcnt_hi((unsigned)(bal >> 32), __builtin_amdgcn_mbcnt_lo((unsigned)bal, 0u));
;       if (pred) cand[pos] = key[r];
;       base += __builtin_popcountll(bal);
;     }
.LBB0_686:
	s_mov_b64 s[2:3], -1
	s_and_b64 vcc, exec, s[0:1]
	s_cbranch_vccnz .LBB0_729
	s_cmp_ge_u32 s23, s20
	s_mov_b64 s[0:1], 0
	s_cbranch_scc1 .LBB0_727
	v_cmp_le_u32_e32 vcc, s23, v10
	v_cmp_ge_u32_e64 s[0:1], s20, v10
	s_and_b64 vcc, vcc, s[0:1]
	s_and_saveexec_b64 s[0:1], vcc
	v_mbcnt_lo_u32_b32 v18, vcc_lo, 0
	v_mbcnt_hi_u32_b32 v18, vcc_hi, v18
	v_lshl_add_u32 v18, v18, 2, s15
	ds_write_b32 v18, v10
	s_or_b64 exec, exec, s[0:1]
	s_bcnt1_i32_b64 s4, vcc
	v_cmp_le_u32_e32 vcc, s23, v3
	v_cmp_ge_u32_e64 s[0:1], s20, v3
	s_and_b64 vcc, vcc, s[0:1]
	s_and_saveexec_b64 s[0:1], vcc
	v_mbcnt_lo_u32_b32 v18, vcc_lo, 0
	s_lshl_b32 s6, s4, 2
	v_mbcnt_hi_u32_b32 v18, vcc_hi, v18
	s_add_i32 s6, s6, s15
	v_lshl_add_u32 v18, v18, 2, s6
	ds_write_b32 v18, v3
.LBB0_692:
	s_or_b64 exec, exec, s[0:1]
	s_bcnt1_i32_b64 s0, vcc
	s_add_i32 s4, s0, s4
	v_cmp_le_u32_e32 vcc, s23, v2
	v_cmp_ge_u32_e64 s[0:1], s20, v2
	s_and_b64 vcc, vcc, s[0:1]
	s_and_saveexec_b64 s[0:1], vcc
	v_mbcnt_lo_u32_b32 v18, vcc_lo, 0
	s_lshl_b32 s6, s4, 2
	v_mbcnt_hi_u32_b32 v18, vcc_hi, v18
	s_add_i32 s6, s6, s15
	v_lshl_add_u32 v18, v18, 2, s6
	ds_write_b32 v18, v2
.LBB0_694:
	s_or_b64 exec, exec, s[0:1]
	s_bcnt1_i32_b64 s0, vcc
	s_add_i32 s4, s4, s0
	v_cmp_le_u32_e32 vcc, s23, v5
	v_cmp_ge_u32_e64 s[0:1], s20, v5
	s_and_b64 vcc, vcc, s[0:1]
	s_and_saveexec_b64 s[0:1], vcc
	v_mbcnt_lo_u32_b32 v18, vcc_lo, 0
	s_lshl_b32 s6, s4, 2
	v_mbcnt_hi_u32_b32 v18, vcc_hi, v18
	s_add_i32 s6, s6, s15
	v_lshl_add_u32 v18, v18, 2, s6
	ds_write_b32 v18, v5
.LBB0_696:
	s_or_b64 exec, exec, s[0:1]
	s_bcnt1_i32_b64 s0, vcc
	s_add_i32 s4, s4, s0
	v_cmp_le_u32_e32 vcc, s23, v4
	v_cmp_ge_u32_e64 s[0:1], s20, v4
	s_and_b64 vcc, vcc, s[0:1]
	s_and_saveexec_b64 s[0:1], vcc
	v_mbcnt_lo_u32_b32 v18, vcc_lo, 0
	s_lshl_b32 s6, s4, 2
	v_mbcnt_hi_u32_b32 v18, vcc_hi, v18
	s_add_i32 s6, s6, s15
	v_lshl_add_u32 v18, v18, 2, s6
	ds_write_b32 v18, v4
.LBB0_698:
	s_or_b64 exec, exec, s[0:1]
	s_bcnt1_i32_b64 s0, vcc
	s_add_i32 s4, s4, s0
	v_cmp_le_u32_e32 vcc, s23, v7
	v_cmp_ge_u32_e64 s[0:1], s20, v7
	s_and_b64 vcc, vcc, s[0:1]
	s_and_saveexec_b64 s[0:1], vcc
	v_mbcnt_lo_u32_b32 v18, vcc_lo, 0
	s_lshl_b32 s6, s4, 2
	v_mbcnt_hi_u32_b32 v18, vcc_hi, v18
	s_add_i32 s6, s6, s15
	v_lshl_add_u32 v18, v18, 2, s6
	ds_write_b32 v18, v7
.LBB0_700:
	s_or_b64 exec, exec, s[0:1]
	s_bcnt1_i32_b64 s0, vcc
	s_add_i32 s4, s4, s0
	v_cmp_le_u32_e32 vcc, s23, v6
	v_cmp_ge_u32_e64 s[0:1], s20, v6
	s_and_b64 vcc, vcc, s[0:1]
	s_and_saveexec_b64 s[0:1], vcc
	v_mbcnt_lo_u32_b32 v18, vcc_lo, 0
	s_lshl_b32 s6, s4, 2
	v_mbcnt_hi_u32_b32 v18, vcc_hi, v18
	s_add_i32 s6, s6, s15
	v_lshl_add_u32 v18, v18, 2, s6
	ds_write_b32 v18, v6
.LBB0_702:
	s_or_b64 exec, exec, s[0:1]
	s_bcnt1_i32_b64 s0, vcc
	s_add_i32 s4, s4, s0
	v_cmp_le_u32_e32 vcc, s23, v9
	v_cmp_ge_u32_e64 s[0:1], s20, v9
	s_and_b64 vcc, vcc, s[0:1]
	s_and_saveexec_b64 s[0:1], vcc
	v_mbcnt_lo_u32_b32 v18, vcc_lo, 0
	s_lshl_b32 s6, s4, 2
	v_mbcnt_hi_u32_b32 v18, vcc_hi, v18
	s_add_i32 s6, s6, s15
	v_lshl_add_u32 v18, v18, 2, s6
	ds_write_b32 v18, v9
.LBB0_704:
	s_or_b64 exec, exec, s[0:1]
	s_bcnt1_i32_b64 s0, vcc
	s_add_i32 s4, s4, s0
	v_cmp_le_u32_e32 vcc, s23, v8
	v_cmp_ge_u32_e64 s[0:1], s20, v8
	s_and_b64 vcc, vcc, s[0:1]
	s_and_saveexec_b64 s[0:1], vcc
	v_mbcnt_lo_u32_b32 v18, vcc_lo, 0
	s_lshl_b32 s6, s4, 2
	v_mbcnt_hi_u32_b32 v18, vcc_hi, v18
	s_add_i32 s6, s6, s15
	v_lshl_add_u32 v18, v18, 2, s6
	ds_write_b32 v18, v8
.LBB0_706:
	s_or_b64 exec, exec, s[0:1]
	s_bcnt1_i32_b64 s0, vcc
	s_add_i32 s4, s4, s0
	v_cmp_le_u32_e32 vcc, s23, v11
	v_cmp_ge_u32_e64 s[0:1], s20, v11
	s_and_b64 vcc, vcc, s[0:1]
	s_and_saveexec_b64 s[0:1], vcc
	v_mbcnt_lo_u32_b32 v18, vcc_lo, 0
	s_lshl_b32 s6, s4, 2
	v_mbcnt_hi_u32_b32 v18, vcc_hi, v18
	s_add_i32 s6, s6, s15
	v_lshl_add_u32 v18, v18, 2, s6
	ds_write_b32 v18, v11
.LBB0_708:
	s_or_b64 exec, exec, s[0:1]
	s_bcnt1_i32_b64 s0, vcc
	s_add_i32 s4, s4, s0
	v_cmp_le_u32_e32 vcc, s23, v12
	v_cmp_ge_u32_e64 s[0:1], s20, v12
	s_and_b64 vcc, vcc, s[0:1]
	s_and_saveexec_b64 s[0:1], vcc
	v_mbcnt_lo_u32_b32 v18, vcc_lo, 0
	s_lshl_b32 s6, s4, 2
	v_mbcnt_hi_u32_b32 v18, vcc_hi, v18
	s_add_i32 s6, s6, s15
	v_lshl_add_u32 v18, v18, 2, s6
	ds_write_b32 v18, v12
.LBB0_710:
	s_or_b64 exec, exec, s[0:1]
	s_bcnt1_i32_b64 s0, vcc
	s_add_i32 s4, s4, s0
	v_cmp_le_u32_e32 vcc, s23, v13
	v_cmp_ge_u32_e64 s[0:1], s20, v13
	s_and_b64 vcc, vcc, s[0:1]
	s_and_saveexec_b64 s[0:1], vcc
	v_mbcnt_lo_u32_b32 v18, vcc_lo, 0
	s_lshl_b32 s6, s4, 2
	v_mbcnt_hi_u32_b32 v18, vcc_hi, v18
	s_add_i32 s6, s6, s15
	v_lshl_add_u32 v18, v18, 2, s6
	ds_write_b32 v18, v13
.LBB0_712:
	s_or_b64 exec, exec, s[0:1]
	s_bcnt1_i32_b64 s0, vcc
	s_add_i32 s4, s4, s0
	v_cmp_le_u32_e32 vcc, s23, v14
	v_cmp_ge_u32_e64 s[0:1], s20, v14
	s_and_b64 vcc, vcc, s[0:1]
	s_and_saveexec_b64 s[0:1], vcc
	v_mbcnt_lo_u32_b32 v18, vcc_lo, 0
	s_lshl_b32 s6, s4, 2
	v_mbcnt_hi_u32_b32 v18, vcc_hi, v18
	s_add_i32 s6, s6, s15
	v_lshl_add_u32 v18, v18, 2, s6
	ds_write_b32 v18, v14
.LBB0_714:
	s_or_b64 exec, exec, s[0:1]
	s_bcnt1_i32_b64 s0, vcc
	s_add_i32 s4, s4, s0
	v_cmp_le_u32_e32 vcc, s23, v15
	v_cmp_ge_u32_e64 s[0:1], s20, v15
	s_and_b64 vcc, vcc, s[0:1]
	s_and_saveexec_b64 s[0:1], vcc
	v_mbcnt_lo_u32_b32 v18, vcc_lo, 0
	s_lshl_b32 s6, s4, 2
	v_mbcnt_hi_u32_b32 v18, vcc_hi, v18
	s_add_i32 s6, s6, s15
	v_lshl_add_u32 v18, v18, 2, s6
	ds_write_b32 v18, v15
.LBB0_716:
	s_or_b64 exec, exec, s[0:1]
	s_bcnt1_i32_b64 s0, vcc
	s_add_i32 s4, s4, s0
	v_cmp_le_u32_e32 vcc, s23, v16
	v_cmp_ge_u32_e64 s[0:1], s20, v16
	s_and_b64 vcc, vcc, s[0:1]
	s_and_saveexec_b64 s[0:1], vcc
	v_mbcnt_lo_u32_b32 v18, vcc_lo, 0
	s_lshl_b32 s6, s4, 2
	v_mbcnt_hi_u32_b32 v18, vcc_hi, v18
	s_add_i32 s6, s6, s15
	v_lshl_add_u32 v18, v18, 2, s6
	ds_write_b32 v18, v16

; DI unsigned fkey(float f) { unsigned u = __float_as_uint(f); return (u & 0x80000000u) ? ~u : (u | 0x80000000u); }
; DI float funkey(unsigned k) { return __uint_as_float((k & 0x80000000u) ? (k ^ 0x80000000u) : ~k); }
; template <int NR>
; DI u64 select_wave(float* scw, int nreg, int lane) {
;   unsigned key[NR];
;   unsigned kmin = 0xffffffffu, kmax = 0u;
; #pragma unroll
;   for (int r = 0; r < NR; ++r) {
;     const unsigned k = fkey(scw[64 * r + lane]);
;     const bool ok = r < nreg;
;     key[r] = ok ? k : 0u;
;     kmin = min(kmin, ok ? k : 0xffffffffu); kmax = max(kmax, key[r]);
;   }
; #pragma unroll
;   for (int o = 1; o < 64; o <<= 1) { kmin = min(kmin, (unsigned)__shfl_xor((int)kmin, o)); kmax = max(kmax, (unsigned)__shfl_xor((int)kmax, o)); }
;   unsigned lo = __builtin_amdgcn_readfirstlane(kmin), hi = __builtin_amdgcn_readfirstlane(kmax);
;   int clo = 64 * nreg, chi = 0;
;   bool exact = false;
;   int iter = 0;
;   while (lo < hi && clo - chi > 512) {
;     unsigned mid = fkey(0.5f * (funkey(lo) + funkey(hi)));
;     if (iter >= 16) mid = lo + ((hi - lo + 1u) >> 1);
;     if (mid <= lo) mid = lo + 1;
;     if (mid > hi) mid = hi;
;     ++iter;
;     int cnt = 0;
; #pragma unroll
;     for (int r = 0; r < NR; ++r) cnt += __builtin_popcountll(__builtin_amdgcn_ballot_w64(key[r] >= mid));
;     if (cnt >= 256) { lo = mid; clo = cnt; if (cnt == 256) { exact = true; break; } }
;     else { hi = mid - 1; chi = cnt; }
;   }
;   if (!exact && lo < hi) {
;     unsigned* cand = reinterpret_cast<unsigned*>(scw);
;     int base = 0;
; #pragma unroll
;     for (int r = 0; r < NR; ++r) {
;       const bool pred = (key[r] >= lo) && (key[r] <= hi);
;       const u64 bal = __builtin_amdgcn_ballot_w64(pred);
;       const int pos = base + __builtin_amdgcn_mbcnt_hi((unsigned)(bal >> 32), __builtin_amdgcn_mbcnt_lo((unsigned)bal, 0u));
;       if (pred) cand[pos] = key[r];
;       base += __builtin_popcountll(bal);
;     }
.LBB0_733:
	s_andn2_b64 vcc, exec, s[0:1]
	s_cbranch_vccnz .LBB0_759
	ds_read2st64_b32 v[2:3], v87 offset1:1
	s_cmp_eq_u32 s47, 0
	s_waitcnt lgkmcnt(0)
	v_not_b32_e32 v4, v2
	v_or_b32_e32 v5, 0x80000000, v2
	v_cmp_gt_i32_e32 vcc, 0, v2
	s_nop 1
	v_cndmask_b32_e32 v2, v5, v4, vcc
	v_not_b32_e32 v4, v3
	v_or_b32_e32 v5, 0x80000000, v3
	v_cmp_gt_i32_e32 vcc, 0, v3
	s_nop 1
	v_cndmask_b32_e32 v4, v5, v4, vcc
	s_cselect_b64 vcc, -1, 0
	v_cndmask_b32_e64 v3, v4, 0, vcc
	v_min_u32_e32 v4, v2, v4
	v_cndmask_b32_e32 v6, v4, v2, vcc
	ds_read2st64_b32 v[4:5], v87 offset0:2 offset1:3
	v_max_u32_e32 v10, v2, v3
	s_cmpk_gt_u32 s28, 0x13f
	s_waitcnt lgkmcnt(0)
	v_not_b32_e32 v7, v4
	v_or_b32_e32 v8, 0x80000000, v4
	v_cmp_gt_i32_e32 vcc, 0, v4
	v_and_b32_e32 v9, 0x7fffffff, v5
	v_xor_b32_e32 v12, -1, v5
	v_cndmask_b32_e32 v4, v8, v7, vcc
	v_min_u32_e32 v11, v6, v4
	ds_read2st64_b32 v[6:7], v87 offset0:4 offset1:5
	v_cmp_gt_i32_e64 s[0:1], 0, v5
	s_waitcnt lgkmcnt(0)
	v_and_b32_e32 v8, 0x7fffffff, v6
	v_xor_b32_e32 v13, -1, v6
	v_pk_add_f32 v[8:9], v[8:9], 0 neg_lo:[1,1] neg_hi:[1,1]
	v_cmp_gt_i32_e32 vcc, 0, v6
	v_cndmask_b32_e64 v6, v9, v12, s[0:1]
	s_mov_b64 s[0:1], 0
	v_cndmask_b32_e32 v5, v8, v13, vcc
	v_max3_u32 v8, v10, v4, v6
	v_min3_u32 v9, v11, v6, v5
	v_not_b32_e32 v10, v7
	v_or_b32_e32 v11, 0x80000000, v7
	v_cmp_gt_i32_e32 vcc, 0, v7
	s_nop 1
	v_cndmask_b32_e32 v10, v11, v10, vcc
	s_cselect_b64 vcc, -1, 0
	v_cndmask_b32_e32 v7, 0, v10, vcc
	v_min_u32_e32 v10, v9, v10
	v_cndmask_b32_e32 v10, v9, v10, vcc
	v_max3_u32 v11, v8, v5, v7
	ds_read2st64_b32 v[8:9], v87 offset0:6 offset1:7
	s_cmpk_gt_u32 s28, 0x17f
	s_waitcnt lgkmcnt(0)
	v_not_b32_e32 v12, v8
	v_or_b32_e32 v13, 0x80000000, v8
	v_cmp_gt_i32_e32 vcc, 0, v8
	s_nop 1
	v_cndmask_b32_e32 v12, v13, v12, vcc
	s_cselect_b64 vcc, -1, 0
	v_cndmask_b32_e32 v8, 0, v12, vcc
	v_min_u32_e32 v12, v10, v12
	v_cndmask_b32_e32 v10, v10, v12, vcc
	v_not_b32_e32 v12, v9
	v_or_b32_e32 v13, 0x80000000, v9
	v_cmp_gt_i32_e32 vcc, 0, v9
	s_cmpk_gt_u32 s28, 0x1bf
	s_nop 0
	v_cndmask_b32_e32 v12, v13, v12, vcc
	s_cselect_b64 vcc, -1, 0
	v_cndmask_b32_e32 v9, 0, v12, vcc
	v_min_u32_e32 v12, v10, v12
	v_cndmask_b32_e32 v10, v10, v12, vcc
	v_max3_u32 v11, v11, v8, v9
	s_waitcnt lgkmcnt(0)
	s_nop 1
	v_min_u32_dpp v10, v10, v10 quad_perm:[1,0,3,2] row_mask:0xf bank_mask:0xf
	v_max_u32_dpp v11, v11, v11 quad_perm:[1,0,3,2] row_mask:0xf bank_mask:0xf
	s_nop 0
	v_min_u32_dpp v10, v10, v10 quad_perm:[2,3,0,1] row_mask:0xf bank_mask:0xf
	v_max_u32_dpp v11, v11, v11 quad_perm:[2,3,0,1] row_mask:0xf bank_mask:0xf
	s_nop 0
	v_min_u32_dpp v10, v10, v10 row_half_mirror row_mask:0xf bank_mask:0xf
	v_max_u32_dpp v11, v11, v11 row_half_mirror row_mask:0xf bank_mask:0xf
	s_nop 0
	v_min_u32_dpp v10, v10, v10 row_mirror row_mask:0xf bank_mask:0xf
	v_max_u32_dpp v11, v11, v11 row_mirror row_mask:0xf bank_mask:0xf
	s_nop 0
	v_min_u32_dpp v10, v10, v10 row_bcast:15 row_mask:0xa bank_mask:0xf
	v_max_u32_dpp v11, v11, v11 row_bcast:15 row_mask:0xa bank_mask:0xf
	s_nop 0
	v_min_u32_dpp v10, v10, v10 row_bcast:31 row_mask:0xc bank_mask:0xf
	v_max_u32_dpp v11, v11, v11 row_bcast:31 row_mask:0xc bank_mask:0xf
	s_nop 0
	v_readlane_b32 s23, v10, 63
	v_readlane_b32 s22, v11, 63
	s_cmp_ge_u32 s23, s22
	s_cbranch_scc1 .LBB0_755
	v_cmp_le_u32_e32 vcc, s23, v2
	v_cmp_ge_u32_e64 s[0:1], s22, v2
	s_and_b64 vcc, vcc, s[0:1]
	s_and_saveexec_b64 s[0:1], vcc
	v_mbcnt_lo_u32_b32 v10, vcc_lo, 0
	v_mbcnt_hi_u32_b32 v10, vcc_hi, v10
	v_lshl_add_u32 v10, v10, 2, s15
	ds_write_b32 v10, v2
	s_or_b64 exec, exec, s[0:1]
	s_bcnt1_i32_b64 s2, vcc
	v_cmp_le_u32_e32 vcc, s23, v3
	v_cmp_ge_u32_e64 s[0:1], s22, v3
	s_and_b64 vcc, vcc, s[0:1]
	s_and_saveexec_b64 s[0:1], vcc
	v_mbcnt_lo_u32_b32 v10, vcc_lo, 0
	s_lshl_b32 s3, s2, 2
	v_mbcnt_hi_u32_b32 v10, vcc_hi, v10
	s_add_i32 s3, s3, s15
	v_lshl_add_u32 v10, v10, 2, s3
	ds_write_b32 v10, v3
.LBB0_739:
	s_or_b64 exec, exec, s[0:1]
	s_bcnt1_i32_b64 s0, vcc
	s_add_i32 s2, s0, s2
	v_cmp_le_u32_e32 vcc, s23, v4
	v_cmp_ge_u32_e64 s[0:1], s22, v4
	s_and_b64 vcc, vcc, s[0:1]
	s_and_saveexec_b64 s[0:1], vcc
	v_mbcnt_lo_u32_b32 v10, vcc_lo, 0
	s_lshl_b32 s3, s2, 2
	v_mbcnt_hi_u32_b32 v10, vcc_hi, v10
	s_add_i32 s3, s3, s15
	v_lshl_add_u32 v10, v10, 2, s3
	ds_write_b32 v10, v4
.LBB0_741:
	s_or_b64 exec, exec, s[0:1]
	s_bcnt1_i32_b64 s0, vcc
	s_add_i32 s2, s2, s0
	v_cmp_le_u32_e32 vcc, s23, v6
	v_cmp_ge_u32_e64 s[0:1], s22, v6
	s_and_b64 vcc, vcc, s[0:1]
	s_and_saveexec_b64 s[0:1], vcc
	v_mbcnt_lo_u32_b32 v10, vcc_lo, 0
	s_lshl_b32 s3, s2, 2
	v_mbcnt_hi_u32_b32 v10, vcc_hi, v10
	s_add_i32 s3, s3, s15
	v_lshl_add_u32 v10, v10, 2, s3
	ds_write_b32 v10, v6
.LBB0_743:
	s_or_b64 exec, exec, s[0:1]
	s_bcnt1_i32_b64 s0, vcc
	s_add_i32 s2, s2, s0
	v_cmp_le_u32_e32 vcc, s23, v5
	v_cmp_ge_u32_e64 s[0:1], s22, v5
	s_and_b64 vcc, vcc, s[0:1]
	s_and_saveexec_b64 s[0:1], vcc
	v_mbcnt_lo_u32_b32 v10, vcc_lo, 0
	s_lshl_b32 s3, s2, 2
	v_mbcnt_hi_u32_b32 v10, vcc_hi, v10
	s_add_i32 s3, s3, s15
	v_lshl_add_u32 v10, v10, 2, s3
	ds_write_b32 v10, v5
.LBB0_745:
	s_or_b64 exec, exec, s[0:1]
	s_bcnt1_i32_b64 s0, vcc
	s_add_i32 s2, s2, s0
	v_cmp_le_u32_e32 vcc, s23, v7
	v_cmp_ge_u32_e64 s[0:1], s22, v7
	s_and_b64 vcc, vcc, s[0:1]
	s_and_saveexec_b64 s[0:1], vcc
	v_mbcnt_lo_u32_b32 v10, vcc_lo, 0
	s_lshl_b32 s3, s2, 2
	v_mbcnt_hi_u32_b32 v10, vcc_hi, v10
	s_add_i32 s3, s3, s15
	v_lshl_add_u32 v10, v10, 2, s3
	ds_write_b32 v10, v7
.LBB0_747:
	s_or_b64 exec, exec, s[0:1]
	s_bcnt1_i32_b64 s0, vcc
	s_add_i32 s2, s2, s0
	v_cmp_le_u32_e32 vcc, s23, v8
	v_cmp_ge_u32_e64 s[0:1], s22, v8
	s_and_b64 vcc, vcc, s[0:1]
	s_and_saveexec_b64 s[0:1], vcc
	v_mbcnt_lo_u32_b32 v10, vcc_lo, 0
	s_lshl_b32 s3, s2, 2
	v_mbcnt_hi_u32_b32 v10, vcc_hi, v10
	s_add_i32 s3, s3, s15
	v_lshl_add_u32 v10, v10, 2, s3
	ds_write_b32 v10, v8
